# prep phase: adaLN k-loop software-pipelined (64 nt loads in flight), silu inputs loaded up front, cache K/V conversion unrolled (grid==512 fast path, original loop kept as fallback); peer_apply L1 LN2
# speedup vs baseline: 1.0263x; 1.0047x over previous
.LBB0_56:
	s_or_b64 exec, exec, s[16:17]
	s_mov_b64 s[4:5], 0x100000
	v_cmp_gt_u64_e32 vcc, s[4:5], v[4:5]
	s_and_saveexec_b64 s[4:5], vcc
	s_cbranch_execz .LBB0_59
	s_add_u32 s6, s42, 0xd324000
	s_addc_u32 s7, s43, 0
	s_add_u32 s16, s42, 0xdd24800
	s_addc_u32 s17, s43, 0
	v_and_b32_e32 v8, 63, v2
	v_mov_b32_e32 v7, 0
	s_lshl_b64 s[8:9], s[66:67], 10
	v_lshl_add_u64 v[10:11], s[8:9], 0, v[6:7]
	s_lshl_b64 s[8:9], s[2:3], 10
	s_mov_b64 s[10:11], 0
	s_movk_i32 s3, 0x600
	v_lshlrev_b32_e32 v12, 1, v8
	v_mov_b32_e32 v13, v7
	s_mov_b32 s18, 0x80000
	s_movk_i32 s19, 0xc00
	v_mov_b64_e32 v[14:15], s[16:17]
	s_mov_b64 s[16:17], 0xfffff
	s_cmp_eq_u32 s2, 0x200
	s_cbranch_scc0 .Lcache_orig
	v_and_b32_e32 v116, 0x3ff, v0
	v_lshl_or_b32 v116, s66, 8, v116
	v_lshlrev_b32_e32 v117, 2, v116
	v_bfe_u32 v120, v116, 8, 9
	v_lshlrev_b32_e32 v118, 9, v120
	v_and_b32_e32 v119, 0xff, v116
	v_lshl_add_u32 v118, v119, 1, v118
	v_add_u32_e32 v118, 0x80000, v118
	v_mul_u32_u24_e32 v119, 0xc00, v119
	v_lshl_add_u32 v119, v120, 1, v119
	v_add_u32_e32 v119, 0x800, v119
	s_mov_b64 s[98:99], s[52:53]
	s_mov_b64 s[100:101], s[54:55]
	global_load_dword v100, v117, s[98:99]
	global_load_dword v108, v117, s[100:101]
	s_add_u32 s98, s98, 0x80000
	s_addc_u32 s99, s99, 0
	s_add_u32 s100, s100, 0x80000
	s_addc_u32 s101, s101, 0
	global_load_dword v101, v117, s[98:99]
	global_load_dword v109, v117, s[100:101]
	s_add_u32 s98, s98, 0x80000
	s_addc_u32 s99, s99, 0
	s_add_u32 s100, s100, 0x80000
	s_addc_u32 s101, s101, 0
	global_load_dword v102, v117, s[98:99]
	global_load_dword v110, v117, s[100:101]
	s_add_u32 s98, s98, 0x80000
	s_addc_u32 s99, s99, 0
	s_add_u32 s100, s100, 0x80000
	s_addc_u32 s101, s101, 0
	global_load_dword v103, v117, s[98:99]
	global_load_dword v111, v117, s[100:101]
	s_add_u32 s98, s98, 0x80000
	s_addc_u32 s99, s99, 0
	s_add_u32 s100, s100, 0x80000
	s_addc_u32 s101, s101, 0
	global_load_dword v104, v117, s[98:99]
	global_load_dword v112, v117, s[100:101]
	s_add_u32 s98, s98, 0x80000
	s_addc_u32 s99, s99, 0
	s_add_u32 s100, s100, 0x80000
	s_addc_u32 s101, s101, 0
	global_load_dword v105, v117, s[98:99]
	global_load_dword v113, v117, s[100:101]
	s_add_u32 s98, s98, 0x80000
	s_addc_u32 s99, s99, 0
	s_add_u32 s100, s100, 0x80000
	s_addc_u32 s101, s101, 0
	global_load_dword v106, v117, s[98:99]
	global_load_dword v114, v117, s[100:101]
	s_add_u32 s98, s98, 0x80000
	s_addc_u32 s99, s99, 0
	s_add_u32 s100, s100, 0x80000
	s_addc_u32 s101, s101, 0
	global_load_dword v107, v117, s[98:99]
	global_load_dword v115, v117, s[100:101]
	s_add_u32 s98, s42, 0xd324000
	s_addc_u32 s99, s43, 0
	s_add_u32 s100, s42, 0xdd24000
	s_addc_u32 s101, s43, 0
	s_waitcnt vmcnt(14)
	v_cvt_pk_bf16_f32 v100, v100, v100
	v_cvt_pk_bf16_f32 v108, v108, v108
	v_add_u32_e32 v120, 0x0, v118
	global_store_short v120, v100, s[98:99]
	v_add_u32_e32 v116, 0x0, v119
	global_store_short v116, v108, s[100:101]
	s_waitcnt vmcnt(14)
	v_cvt_pk_bf16_f32 v101, v101, v101
	v_cvt_pk_bf16_f32 v109, v109, v109
	v_add_u32_e32 v120, 0x300000, v118
	global_store_short v120, v101, s[98:99]
	v_add_u32_e32 v116, 0x300000, v119
	global_store_short v116, v109, s[100:101]
	s_waitcnt vmcnt(14)
	v_cvt_pk_bf16_f32 v102, v102, v102
	v_cvt_pk_bf16_f32 v110, v110, v110
	v_add_u32_e32 v120, 0xc0000, v118
	global_store_short v120, v102, s[98:99]
	v_add_u32_e32 v116, 0xc0000, v119
	global_store_short v116, v110, s[100:101]
	s_waitcnt vmcnt(14)
	v_cvt_pk_bf16_f32 v103, v103, v103
	v_cvt_pk_bf16_f32 v111, v111, v111
	v_add_u32_e32 v120, 0x3c0000, v118
	global_store_short v120, v103, s[98:99]
	v_add_u32_e32 v116, 0x3c0000, v119
	global_store_short v116, v111, s[100:101]
	s_waitcnt vmcnt(14)
	v_cvt_pk_bf16_f32 v104, v104, v104
	v_cvt_pk_bf16_f32 v112, v112, v112
	v_add_u32_e32 v120, 0x180000, v118
	global_store_short v120, v104, s[98:99]
	v_add_u32_e32 v116, 0x180000, v119
	global_store_short v116, v112, s[100:101]
	s_waitcnt vmcnt(14)
	v_cvt_pk_bf16_f32 v105, v105, v105
	v_cvt_pk_bf16_f32 v113, v113, v113
	v_add_u32_e32 v120, 0x480000, v118
	global_store_short v120, v105, s[98:99]
	v_add_u32_e32 v116, 0x480000, v119
	global_store_short v116, v113, s[100:101]
	s_waitcnt vmcnt(14)
	v_cvt_pk_bf16_f32 v106, v106, v106
	v_cvt_pk_bf16_f32 v114, v114, v114
	v_add_u32_e32 v120, 0x240000, v118
	global_store_short v120, v106, s[98:99]
	v_add_u32_e32 v116, 0x240000, v119
	global_store_short v116, v114, s[100:101]
	s_waitcnt vmcnt(14)
	v_cvt_pk_bf16_f32 v107, v107, v107
	v_cvt_pk_bf16_f32 v115, v115, v115
	v_add_u32_e32 v120, 0x540000, v118
	global_store_short v120, v107, s[98:99]
	v_add_u32_e32 v116, 0x540000, v119
	global_store_short v116, v115, s[100:101]
	s_branch .LBB0_59
.Lcache_orig:
.LBB0_58:
	v_lshl_add_u64 v[16:17], s[52:53], 0, v[10:11]
	v_lshl_add_u64 v[18:19], s[54:55], 0, v[10:11]
	global_load_dword v1, v[16:17], off
	global_load_dword v3, v[18:19], off
	v_lshrrev_b64 v[16:17], 18, v[4:5]
	v_lshrrev_b32_e32 v6, 15, v4
	v_and_or_b32 v16, v6, 4, v16
	v_bfe_u32 v22, v4, 8, 9
	v_lshrrev_b32_e32 v20, 18, v5
	v_mad_u64_u32 v[18:19], s[20:21], v16, s3, 0
	v_and_b32_e32 v9, 0xc0, v4
	v_lshlrev_b64 v[16:17], 8, v[16:17]
	v_mad_u32_u24 v19, v20, s3, v19
	v_or_b32_e32 v18, v18, v22
	v_lshlrev_b32_e32 v6, 1, v9
	v_or3_b32 v9, v16, v9, v8
	v_lshlrev_b64 v[18:19], 9, v[18:19]
	v_mad_u64_u32 v[20:21], s[20:21], v9, s19, v[14:15]
	v_lshl_add_u64 v[18:19], s[6:7], 0, v[18:19]
	v_lshl_add_u64 v[4:5], v[4:5], 0, s[14:15]
	v_mad_u32_u24 v21, v17, s19, v21
	v_lshl_add_u64 v[16:17], v[18:19], 0, v[6:7]
	v_cmp_lt_u64_e32 vcc, s[16:17], v[4:5]
	v_lshl_add_u64 v[16:17], v[16:17], 0, v[12:13]
	s_or_b64 s[10:11], vcc, s[10:11]
	v_add_co_u32_e32 v16, vcc, s18, v16
	v_lshl_add_u64 v[10:11], v[10:11], 0, s[8:9]
	v_lshlrev_b32_e32 v6, 1, v22
	v_addc_co_u32_e32 v17, vcc, 0, v17, vcc
	v_lshl_add_u64 v[18:19], v[20:21], 0, v[6:7]
	s_waitcnt vmcnt(1)
	v_cvt_pk_bf16_f32 v1, v1, s0
	s_waitcnt vmcnt(0)
	v_cvt_pk_bf16_f32 v3, v3, s0
	global_store_short v[16:17], v1, off
	global_store_short v[18:19], v3, off
	s_andn2_b64 exec, exec, s[10:11]
	s_cbranch_execnz .LBB0_58

.LBB0_62:
	s_mov_b64 s[8:9], 0
	v_mov_b32_e32 v13, v22
	v_mov_b32_e32 v16, v2
	s_barrier
	v_and_b32_e32 v126, 0x3ff, v0
	v_lshlrev_b32_e32 v126, 2, v126
	global_load_dword v100, v126, s[60:61] offset:0
	global_load_dword v101, v126, s[60:61] offset:1024
	global_load_dword v102, v126, s[60:61] offset:2048
	global_load_dword v103, v126, s[60:61] offset:3072
	s_mov_b64 s[98:99], s[58:59]
	global_load_dword v104, v126, s[98:99] offset:0
	global_load_dword v105, v126, s[98:99] offset:1024
	global_load_dword v106, v126, s[98:99] offset:2048
	global_load_dword v107, v126, s[98:99] offset:3072
	s_add_u32 s98, s98, 0x1000
	s_addc_u32 s99, s99, 0
	global_load_dword v108, v126, s[98:99] offset:0
	global_load_dword v109, v126, s[98:99] offset:1024
	global_load_dword v110, v126, s[98:99] offset:2048
	global_load_dword v111, v126, s[98:99] offset:3072
	s_add_u32 s98, s98, 0x1000
	s_addc_u32 s99, s99, 0
	global_load_dword v112, v126, s[98:99] offset:0
	global_load_dword v113, v126, s[98:99] offset:1024
	global_load_dword v114, v126, s[98:99] offset:2048
	global_load_dword v115, v126, s[98:99] offset:3072
	s_add_u32 s98, s98, 0x1000
	s_addc_u32 s99, s99, 0
	global_load_dword v116, v126, s[98:99] offset:0
	global_load_dword v117, v126, s[98:99] offset:1024
	global_load_dword v118, v126, s[98:99] offset:2048
	global_load_dword v119, v126, s[98:99] offset:3072
	s_waitcnt vmcnt(19)
	v_mul_f32_e32 v120, 0xbfb8aa3b, v100
	v_exp_f32_e32 v120, v120
	s_nop 0
	v_add_f32_e32 v120, 1.0, v120
	v_div_scale_f32 v121, s[100:101], v120, v120, v100
	v_rcp_f32_e32 v122, v121
	v_div_scale_f32 v123, vcc, v100, v120, v100
	v_fma_f32 v125, -v121, v122, 1.0
	v_fmac_f32_e32 v122, v125, v122
	v_mul_f32_e32 v124, v123, v122
	v_fma_f32 v125, -v121, v124, v123
	v_fmac_f32_e32 v124, v125, v122
	v_fma_f32 v121, -v121, v124, v123
	v_div_fmas_f32 v121, v121, v122, v124
	v_div_fixup_f32 v100, v121, v120, v100
	ds_write_b32 v22, v100 offset:0
	s_waitcnt vmcnt(18)
	v_mul_f32_e32 v120, 0xbfb8aa3b, v101
	v_exp_f32_e32 v120, v120
	s_nop 0
	v_add_f32_e32 v120, 1.0, v120
	v_div_scale_f32 v121, s[100:101], v120, v120, v101
	v_rcp_f32_e32 v122, v121
	v_div_scale_f32 v123, vcc, v101, v120, v101
	v_fma_f32 v125, -v121, v122, 1.0
	v_fmac_f32_e32 v122, v125, v122
	v_mul_f32_e32 v124, v123, v122
	v_fma_f32 v125, -v121, v124, v123
	v_fmac_f32_e32 v124, v125, v122
	v_fma_f32 v121, -v121, v124, v123
	v_div_fmas_f32 v121, v121, v122, v124
	v_div_fixup_f32 v101, v121, v120, v101
	ds_write_b32 v22, v101 offset:1024
	s_waitcnt vmcnt(17)
	v_mul_f32_e32 v120, 0xbfb8aa3b, v102
	v_exp_f32_e32 v120, v120
	s_nop 0
	v_add_f32_e32 v120, 1.0, v120
	v_div_scale_f32 v121, s[100:101], v120, v120, v102
	v_rcp_f32_e32 v122, v121
	v_div_scale_f32 v123, vcc, v102, v120, v102
	v_fma_f32 v125, -v121, v122, 1.0
	v_fmac_f32_e32 v122, v125, v122
	v_mul_f32_e32 v124, v123, v122
	v_fma_f32 v125, -v121, v124, v123
	v_fmac_f32_e32 v124, v125, v122
	v_fma_f32 v121, -v121, v124, v123
	v_div_fmas_f32 v121, v121, v122, v124
	v_div_fixup_f32 v102, v121, v120, v102
	ds_write_b32 v22, v102 offset:2048
	s_waitcnt vmcnt(16)
	v_mul_f32_e32 v120, 0xbfb8aa3b, v103
	v_exp_f32_e32 v120, v120
	s_nop 0
	v_add_f32_e32 v120, 1.0, v120
	v_div_scale_f32 v121, s[100:101], v120, v120, v103
	v_rcp_f32_e32 v122, v121
	v_div_scale_f32 v123, vcc, v103, v120, v103
	v_fma_f32 v125, -v121, v122, 1.0
	v_fmac_f32_e32 v122, v125, v122
	v_mul_f32_e32 v124, v123, v122
	v_fma_f32 v125, -v121, v124, v123
	v_fmac_f32_e32 v124, v125, v122
	v_fma_f32 v121, -v121, v124, v123
	v_div_fmas_f32 v121, v121, v122, v124
	v_div_fixup_f32 v103, v121, v120, v103
	ds_write_b32 v22, v103 offset:3072
	s_waitcnt vmcnt(15)
	v_mul_f32_e32 v120, 0xbfb8aa3b, v104
	v_exp_f32_e32 v120, v120
	s_nop 0
	v_add_f32_e32 v120, 1.0, v120
	v_div_scale_f32 v121, s[100:101], v120, v120, v104
	v_rcp_f32_e32 v122, v121
	v_div_scale_f32 v123, vcc, v104, v120, v104
	v_fma_f32 v125, -v121, v122, 1.0
	v_fmac_f32_e32 v122, v125, v122
	v_mul_f32_e32 v124, v123, v122
	v_fma_f32 v125, -v121, v124, v123
	v_fmac_f32_e32 v124, v125, v122
	v_fma_f32 v121, -v121, v124, v123
	v_div_fmas_f32 v121, v121, v122, v124
	v_div_fixup_f32 v104, v121, v120, v104
	ds_write_b32 v22, v104 offset:4096
	s_waitcnt vmcnt(14)
	v_mul_f32_e32 v120, 0xbfb8aa3b, v105
	v_exp_f32_e32 v120, v120
	s_nop 0
	v_add_f32_e32 v120, 1.0, v120
	v_div_scale_f32 v121, s[100:101], v120, v120, v105
	v_rcp_f32_e32 v122, v121
	v_div_scale_f32 v123, vcc, v105, v120, v105
	v_fma_f32 v125, -v121, v122, 1.0
	v_fmac_f32_e32 v122, v125, v122
	v_mul_f32_e32 v124, v123, v122
	v_fma_f32 v125, -v121, v124, v123
	v_fmac_f32_e32 v124, v125, v122
	v_fma_f32 v121, -v121, v124, v123
	v_div_fmas_f32 v121, v121, v122, v124
	v_div_fixup_f32 v105, v121, v120, v105
	ds_write_b32 v22, v105 offset:5120
	s_waitcnt vmcnt(13)
	v_mul_f32_e32 v120, 0xbfb8aa3b, v106
	v_exp_f32_e32 v120, v120
	s_nop 0
	v_add_f32_e32 v120, 1.0, v120
	v_div_scale_f32 v121, s[100:101], v120, v120, v106
	v_rcp_f32_e32 v122, v121
	v_div_scale_f32 v123, vcc, v106, v120, v106
	v_fma_f32 v125, -v121, v122, 1.0
	v_fmac_f32_e32 v122, v125, v122
	v_mul_f32_e32 v124, v123, v122
	v_fma_f32 v125, -v121, v124, v123
	v_fmac_f32_e32 v124, v125, v122
	v_fma_f32 v121, -v121, v124, v123
	v_div_fmas_f32 v121, v121, v122, v124
	v_div_fixup_f32 v106, v121, v120, v106
	ds_write_b32 v22, v106 offset:6144
	s_waitcnt vmcnt(12)
	v_mul_f32_e32 v120, 0xbfb8aa3b, v107
	v_exp_f32_e32 v120, v120
	s_nop 0
	v_add_f32_e32 v120, 1.0, v120
	v_div_scale_f32 v121, s[100:101], v120, v120, v107
	v_rcp_f32_e32 v122, v121
	v_div_scale_f32 v123, vcc, v107, v120, v107
	v_fma_f32 v125, -v121, v122, 1.0
	v_fmac_f32_e32 v122, v125, v122
	v_mul_f32_e32 v124, v123, v122
	v_fma_f32 v125, -v121, v124, v123
	v_fmac_f32_e32 v124, v125, v122
	v_fma_f32 v121, -v121, v124, v123
	v_div_fmas_f32 v121, v121, v122, v124
	v_div_fixup_f32 v107, v121, v120, v107
	ds_write_b32 v22, v107 offset:7168
	s_waitcnt vmcnt(11)
	v_mul_f32_e32 v120, 0xbfb8aa3b, v108
	v_exp_f32_e32 v120, v120
	s_nop 0
	v_add_f32_e32 v120, 1.0, v120
	v_div_scale_f32 v121, s[100:101], v120, v120, v108
	v_rcp_f32_e32 v122, v121
	v_div_scale_f32 v123, vcc, v108, v120, v108
	v_fma_f32 v125, -v121, v122, 1.0
	v_fmac_f32_e32 v122, v125, v122
	v_mul_f32_e32 v124, v123, v122
	v_fma_f32 v125, -v121, v124, v123
	v_fmac_f32_e32 v124, v125, v122
	v_fma_f32 v121, -v121, v124, v123
	v_div_fmas_f32 v121, v121, v122, v124
	v_div_fixup_f32 v108, v121, v120, v108
	ds_write_b32 v22, v108 offset:8192
	s_waitcnt vmcnt(10)
	v_mul_f32_e32 v120, 0xbfb8aa3b, v109
	v_exp_f32_e32 v120, v120
	s_nop 0
	v_add_f32_e32 v120, 1.0, v120
	v_div_scale_f32 v121, s[100:101], v120, v120, v109
	v_rcp_f32_e32 v122, v121
	v_div_scale_f32 v123, vcc, v109, v120, v109
	v_fma_f32 v125, -v121, v122, 1.0
	v_fmac_f32_e32 v122, v125, v122
	v_mul_f32_e32 v124, v123, v122
	v_fma_f32 v125, -v121, v124, v123
	v_fmac_f32_e32 v124, v125, v122
	v_fma_f32 v121, -v121, v124, v123
	v_div_fmas_f32 v121, v121, v122, v124
	v_div_fixup_f32 v109, v121, v120, v109
	ds_write_b32 v22, v109 offset:9216
	s_waitcnt vmcnt(9)
	v_mul_f32_e32 v120, 0xbfb8aa3b, v110
	v_exp_f32_e32 v120, v120
	s_nop 0
	v_add_f32_e32 v120, 1.0, v120
	v_div_scale_f32 v121, s[100:101], v120, v120, v110
	v_rcp_f32_e32 v122, v121
	v_div_scale_f32 v123, vcc, v110, v120, v110
	v_fma_f32 v125, -v121, v122, 1.0
	v_fmac_f32_e32 v122, v125, v122
	v_mul_f32_e32 v124, v123, v122
	v_fma_f32 v125, -v121, v124, v123
	v_fmac_f32_e32 v124, v125, v122
	v_fma_f32 v121, -v121, v124, v123
	v_div_fmas_f32 v121, v121, v122, v124
	v_div_fixup_f32 v110, v121, v120, v110
	ds_write_b32 v22, v110 offset:10240
	s_waitcnt vmcnt(8)
	v_mul_f32_e32 v120, 0xbfb8aa3b, v111
	v_exp_f32_e32 v120, v120
	s_nop 0
	v_add_f32_e32 v120, 1.0, v120
	v_div_scale_f32 v121, s[100:101], v120, v120, v111
	v_rcp_f32_e32 v122, v121
	v_div_scale_f32 v123, vcc, v111, v120, v111
	v_fma_f32 v125, -v121, v122, 1.0
	v_fmac_f32_e32 v122, v125, v122
	v_mul_f32_e32 v124, v123, v122
	v_fma_f32 v125, -v121, v124, v123
	v_fmac_f32_e32 v124, v125, v122
	v_fma_f32 v121, -v121, v124, v123
	v_div_fmas_f32 v121, v121, v122, v124
	v_div_fixup_f32 v111, v121, v120, v111
	ds_write_b32 v22, v111 offset:11264
	s_waitcnt vmcnt(7)
	v_mul_f32_e32 v120, 0xbfb8aa3b, v112
	v_exp_f32_e32 v120, v120
	s_nop 0
	v_add_f32_e32 v120, 1.0, v120
	v_div_scale_f32 v121, s[100:101], v120, v120, v112
	v_rcp_f32_e32 v122, v121
	v_div_scale_f32 v123, vcc, v112, v120, v112
	v_fma_f32 v125, -v121, v122, 1.0
	v_fmac_f32_e32 v122, v125, v122
	v_mul_f32_e32 v124, v123, v122
	v_fma_f32 v125, -v121, v124, v123
	v_fmac_f32_e32 v124, v125, v122
	v_fma_f32 v121, -v121, v124, v123
	v_div_fmas_f32 v121, v121, v122, v124
	v_div_fixup_f32 v112, v121, v120, v112
	ds_write_b32 v22, v112 offset:12288
	s_waitcnt vmcnt(6)
	v_mul_f32_e32 v120, 0xbfb8aa3b, v113
	v_exp_f32_e32 v120, v120
	s_nop 0
	v_add_f32_e32 v120, 1.0, v120
	v_div_scale_f32 v121, s[100:101], v120, v120, v113
	v_rcp_f32_e32 v122, v121
	v_div_scale_f32 v123, vcc, v113, v120, v113
	v_fma_f32 v125, -v121, v122, 1.0
	v_fmac_f32_e32 v122, v125, v122
	v_mul_f32_e32 v124, v123, v122
	v_fma_f32 v125, -v121, v124, v123
	v_fmac_f32_e32 v124, v125, v122
	v_fma_f32 v121, -v121, v124, v123
	v_div_fmas_f32 v121, v121, v122, v124
	v_div_fixup_f32 v113, v121, v120, v113
	ds_write_b32 v22, v113 offset:13312
	s_waitcnt vmcnt(5)
	v_mul_f32_e32 v120, 0xbfb8aa3b, v114
	v_exp_f32_e32 v120, v120
	s_nop 0
	v_add_f32_e32 v120, 1.0, v120
	v_div_scale_f32 v121, s[100:101], v120, v120, v114
	v_rcp_f32_e32 v122, v121
	v_div_scale_f32 v123, vcc, v114, v120, v114
	v_fma_f32 v125, -v121, v122, 1.0
	v_fmac_f32_e32 v122, v125, v122
	v_mul_f32_e32 v124, v123, v122
	v_fma_f32 v125, -v121, v124, v123
	v_fmac_f32_e32 v124, v125, v122
	v_fma_f32 v121, -v121, v124, v123
	v_div_fmas_f32 v121, v121, v122, v124
	v_div_fixup_f32 v114, v121, v120, v114
	ds_write_b32 v22, v114 offset:14336
	s_waitcnt vmcnt(4)
	v_mul_f32_e32 v120, 0xbfb8aa3b, v115
	v_exp_f32_e32 v120, v120
	s_nop 0
	v_add_f32_e32 v120, 1.0, v120
	v_div_scale_f32 v121, s[100:101], v120, v120, v115
	v_rcp_f32_e32 v122, v121
	v_div_scale_f32 v123, vcc, v115, v120, v115
	v_fma_f32 v125, -v121, v122, 1.0
	v_fmac_f32_e32 v122, v125, v122
	v_mul_f32_e32 v124, v123, v122
	v_fma_f32 v125, -v121, v124, v123
	v_fmac_f32_e32 v124, v125, v122
	v_fma_f32 v121, -v121, v124, v123
	v_div_fmas_f32 v121, v121, v122, v124
	v_div_fixup_f32 v115, v121, v120, v115
	ds_write_b32 v22, v115 offset:15360
	s_waitcnt vmcnt(3)
	v_mul_f32_e32 v120, 0xbfb8aa3b, v116
	v_exp_f32_e32 v120, v120
	s_nop 0
	v_add_f32_e32 v120, 1.0, v120
	v_div_scale_f32 v121, s[100:101], v120, v120, v116
	v_rcp_f32_e32 v122, v121
	v_div_scale_f32 v123, vcc, v116, v120, v116
	v_fma_f32 v125, -v121, v122, 1.0
	v_fmac_f32_e32 v122, v125, v122
	v_mul_f32_e32 v124, v123, v122
	v_fma_f32 v125, -v121, v124, v123
	v_fmac_f32_e32 v124, v125, v122
	v_fma_f32 v121, -v121, v124, v123
	v_div_fmas_f32 v121, v121, v122, v124
	v_div_fixup_f32 v116, v121, v120, v116
	ds_write_b32 v22, v116 offset:16384
	s_waitcnt vmcnt(2)
	v_mul_f32_e32 v120, 0xbfb8aa3b, v117
	v_exp_f32_e32 v120, v120
	s_nop 0
	v_add_f32_e32 v120, 1.0, v120
	v_div_scale_f32 v121, s[100:101], v120, v120, v117
	v_rcp_f32_e32 v122, v121
	v_div_scale_f32 v123, vcc, v117, v120, v117
	v_fma_f32 v125, -v121, v122, 1.0
	v_fmac_f32_e32 v122, v125, v122
	v_mul_f32_e32 v124, v123, v122
	v_fma_f32 v125, -v121, v124, v123
	v_fmac_f32_e32 v124, v125, v122
	v_fma_f32 v121, -v121, v124, v123
	v_div_fmas_f32 v121, v121, v122, v124
	v_div_fixup_f32 v117, v121, v120, v117
	ds_write_b32 v22, v117 offset:17408
	s_waitcnt vmcnt(1)
	v_mul_f32_e32 v120, 0xbfb8aa3b, v118
	v_exp_f32_e32 v120, v120
	s_nop 0
	v_add_f32_e32 v120, 1.0, v120
	v_div_scale_f32 v121, s[100:101], v120, v120, v118
	v_rcp_f32_e32 v122, v121
	v_div_scale_f32 v123, vcc, v118, v120, v118
	v_fma_f32 v125, -v121, v122, 1.0
	v_fmac_f32_e32 v122, v125, v122
	v_mul_f32_e32 v124, v123, v122
	v_fma_f32 v125, -v121, v124, v123
	v_fmac_f32_e32 v124, v125, v122
	v_fma_f32 v121, -v121, v124, v123
	v_div_fmas_f32 v121, v121, v122, v124
	v_div_fixup_f32 v118, v121, v120, v118
	ds_write_b32 v22, v118 offset:18432
	s_waitcnt vmcnt(0)
	v_mul_f32_e32 v120, 0xbfb8aa3b, v119
	v_exp_f32_e32 v120, v120
	s_nop 0
	v_add_f32_e32 v120, 1.0, v120
	v_div_scale_f32 v121, s[100:101], v120, v120, v119
	v_rcp_f32_e32 v122, v121
	v_div_scale_f32 v123, vcc, v119, v120, v119
	v_fma_f32 v125, -v121, v122, 1.0
	v_fmac_f32_e32 v122, v125, v122
	v_mul_f32_e32 v124, v123, v122
	v_fma_f32 v125, -v121, v124, v123
	v_fmac_f32_e32 v124, v125, v122
	v_fma_f32 v121, -v121, v124, v123
	v_div_fmas_f32 v121, v121, v122, v124
	v_div_fixup_f32 v119, v121, v120, v119
	ds_write_b32 v22, v119 offset:19456
	s_or_b64 exec, exec, s[8:9]
	s_mul_hi_i32 s8, s25, 0x2aaaaaab
	s_lshr_b32 s9, s8, 31
	s_ashr_i32 s8, s8, 5
	s_add_i32 s8, s8, s9
	s_mul_i32 s9, s8, 0xc0
	s_sub_i32 s9, s25, s9
	s_lshl_b32 s10, s9, 5
	s_ashr_i32 s9, s8, 31
	s_lshl_b64 s[14:15], s[8:9], 10
	v_lshl_add_u64 v[16:17], s[14:15], 0, v[6:7]
	v_mad_u64_u32 v[18:19], s[14:15], v16, s18, v[10:11]
	v_mad_i32_i24 v19, v17, s18, v19
	s_ashr_i32 s11, s10, 31
	v_lshl_add_u64 v[16:17], s[10:11], 2, v[18:19]
	v_mov_b32_e32 v8, 0
	v_lshl_add_u64 v[16:17], v[16:17], 0, v[14:15]
	s_mov_b64 s[14:15], 0
	v_mov_b32_e32 v13, v1
	v_mov_b32_e32 v18, 0
	v_mov_b32_e32 v19, v8
	v_mov_b32_e32 v20, 0
	v_mov_b32_e32 v21, v8
	s_waitcnt lgkmcnt(0)
	s_barrier
	s_mul_i32 s100, s8, 0x1800000
	s_lshl_b32 s101, s10, 2
	s_add_u32 s100, s100, s101
	s_add_u32 s98, s62, s100
	s_addc_u32 s99, s63, 0
	v_and_b32_e32 v205, 0x3ff, v0
	v_lshrrev_b32_e32 v204, 5, v205
	v_mul_u32_u24_e32 v204, 0x300000, v204
	v_and_b32_e32 v205, 31, v205
	v_lshl_add_u32 v204, v205, 2, v204
	v_mov_b32_e32 v8, 0
	v_mov_b32_e32 v21, 0
	v_mov_b32_e32 v20, 0
	v_mov_b32_e32 v19, 0
	v_mov_b32_e32 v18, 0
	global_load_dword v100, v204, s[98:99] nt
	s_add_u32 s98, s98, 0x6000
	s_addc_u32 s99, s99, 0
	global_load_dword v101, v204, s[98:99] nt
	s_add_u32 s98, s98, 0x6000
	s_addc_u32 s99, s99, 0
	global_load_dword v102, v204, s[98:99] nt
	s_add_u32 s98, s98, 0x6000
	s_addc_u32 s99, s99, 0
	global_load_dword v103, v204, s[98:99] nt
	s_add_u32 s98, s98, 0x6000
	s_addc_u32 s99, s99, 0
	global_load_dword v104, v204, s[98:99] nt
	s_add_u32 s98, s98, 0x6000
	s_addc_u32 s99, s99, 0
	global_load_dword v105, v204, s[98:99] nt
	s_add_u32 s98, s98, 0x6000
	s_addc_u32 s99, s99, 0
	global_load_dword v106, v204, s[98:99] nt
	s_add_u32 s98, s98, 0x6000
	s_addc_u32 s99, s99, 0
	global_load_dword v107, v204, s[98:99] nt
	s_add_u32 s98, s98, 0x6000
	s_addc_u32 s99, s99, 0
	global_load_dword v108, v204, s[98:99] nt
	s_add_u32 s98, s98, 0x6000
	s_addc_u32 s99, s99, 0
	global_load_dword v109, v204, s[98:99] nt
	s_add_u32 s98, s98, 0x6000
	s_addc_u32 s99, s99, 0
	global_load_dword v110, v204, s[98:99] nt
	s_add_u32 s98, s98, 0x6000
	s_addc_u32 s99, s99, 0
	global_load_dword v111, v204, s[98:99] nt
	s_add_u32 s98, s98, 0x6000
	s_addc_u32 s99, s99, 0
	global_load_dword v112, v204, s[98:99] nt
	s_add_u32 s98, s98, 0x6000
	s_addc_u32 s99, s99, 0
	global_load_dword v113, v204, s[98:99] nt
	s_add_u32 s98, s98, 0x6000
	s_addc_u32 s99, s99, 0
	global_load_dword v114, v204, s[98:99] nt
	s_add_u32 s98, s98, 0x6000
	s_addc_u32 s99, s99, 0
	global_load_dword v115, v204, s[98:99] nt
	s_add_u32 s98, s98, 0x6000
	s_addc_u32 s99, s99, 0
	global_load_dword v116, v204, s[98:99] nt
	s_add_u32 s98, s98, 0x6000
	s_addc_u32 s99, s99, 0
	global_load_dword v117, v204, s[98:99] nt
	s_add_u32 s98, s98, 0x6000
	s_addc_u32 s99, s99, 0
	global_load_dword v118, v204, s[98:99] nt
	s_add_u32 s98, s98, 0x6000
	s_addc_u32 s99, s99, 0
	global_load_dword v119, v204, s[98:99] nt
	s_add_u32 s98, s98, 0x6000
	s_addc_u32 s99, s99, 0
	global_load_dword v120, v204, s[98:99] nt
	s_add_u32 s98, s98, 0x6000
	s_addc_u32 s99, s99, 0
	global_load_dword v121, v204, s[98:99] nt
	s_add_u32 s98, s98, 0x6000
	s_addc_u32 s99, s99, 0
	global_load_dword v122, v204, s[98:99] nt
	s_add_u32 s98, s98, 0x6000
	s_addc_u32 s99, s99, 0
	global_load_dword v123, v204, s[98:99] nt
	s_add_u32 s98, s98, 0x6000
	s_addc_u32 s99, s99, 0
	global_load_dword v124, v204, s[98:99] nt
	s_add_u32 s98, s98, 0x6000
	s_addc_u32 s99, s99, 0
	global_load_dword v125, v204, s[98:99] nt
	s_add_u32 s98, s98, 0x6000
	s_addc_u32 s99, s99, 0
	global_load_dword v126, v204, s[98:99] nt
	s_add_u32 s98, s98, 0x6000
	s_addc_u32 s99, s99, 0
	global_load_dword v127, v204, s[98:99] nt
	s_add_u32 s98, s98, 0x6000
	s_addc_u32 s99, s99, 0
	global_load_dword v128, v204, s[98:99] nt
	s_add_u32 s98, s98, 0x6000
	s_addc_u32 s99, s99, 0
	global_load_dword v129, v204, s[98:99] nt
	s_add_u32 s98, s98, 0x6000
	s_addc_u32 s99, s99, 0
	global_load_dword v130, v204, s[98:99] nt
	s_add_u32 s98, s98, 0x6000
	s_addc_u32 s99, s99, 0
	global_load_dword v131, v204, s[98:99] nt
	s_add_u32 s98, s98, 0x6000
	s_addc_u32 s99, s99, 0
	global_load_dword v132, v204, s[98:99] nt
	s_add_u32 s98, s98, 0x6000
	s_addc_u32 s99, s99, 0
	global_load_dword v133, v204, s[98:99] nt
	s_add_u32 s98, s98, 0x6000
	s_addc_u32 s99, s99, 0
	global_load_dword v134, v204, s[98:99] nt
	s_add_u32 s98, s98, 0x6000
	s_addc_u32 s99, s99, 0
	global_load_dword v135, v204, s[98:99] nt
	s_add_u32 s98, s98, 0x6000
	s_addc_u32 s99, s99, 0
	global_load_dword v136, v204, s[98:99] nt
	s_add_u32 s98, s98, 0x6000
	s_addc_u32 s99, s99, 0
	global_load_dword v137, v204, s[98:99] nt
	s_add_u32 s98, s98, 0x6000
	s_addc_u32 s99, s99, 0
	global_load_dword v138, v204, s[98:99] nt
	s_add_u32 s98, s98, 0x6000
	s_addc_u32 s99, s99, 0
	global_load_dword v139, v204, s[98:99] nt
	s_add_u32 s98, s98, 0x6000
	s_addc_u32 s99, s99, 0
	global_load_dword v140, v204, s[98:99] nt
	s_add_u32 s98, s98, 0x6000
	s_addc_u32 s99, s99, 0
	global_load_dword v141, v204, s[98:99] nt
	s_add_u32 s98, s98, 0x6000
	s_addc_u32 s99, s99, 0
	global_load_dword v142, v204, s[98:99] nt
	s_add_u32 s98, s98, 0x6000
	s_addc_u32 s99, s99, 0
	global_load_dword v143, v204, s[98:99] nt
	s_add_u32 s98, s98, 0x6000
	s_addc_u32 s99, s99, 0
	global_load_dword v144, v204, s[98:99] nt
	s_add_u32 s98, s98, 0x6000
	s_addc_u32 s99, s99, 0
	global_load_dword v145, v204, s[98:99] nt
	s_add_u32 s98, s98, 0x6000
	s_addc_u32 s99, s99, 0
	global_load_dword v146, v204, s[98:99] nt
	s_add_u32 s98, s98, 0x6000
	s_addc_u32 s99, s99, 0
	global_load_dword v147, v204, s[98:99] nt
	s_add_u32 s98, s98, 0x6000
	s_addc_u32 s99, s99, 0
	global_load_dword v148, v204, s[98:99] nt
	s_add_u32 s98, s98, 0x6000
	s_addc_u32 s99, s99, 0
	global_load_dword v149, v204, s[98:99] nt
	s_add_u32 s98, s98, 0x6000
	s_addc_u32 s99, s99, 0
	global_load_dword v150, v204, s[98:99] nt
	s_add_u32 s98, s98, 0x6000
	s_addc_u32 s99, s99, 0
	global_load_dword v151, v204, s[98:99] nt
	s_add_u32 s98, s98, 0x6000
	s_addc_u32 s99, s99, 0
	global_load_dword v152, v204, s[98:99] nt
	s_add_u32 s98, s98, 0x6000
	s_addc_u32 s99, s99, 0
	global_load_dword v153, v204, s[98:99] nt
	s_add_u32 s98, s98, 0x6000
	s_addc_u32 s99, s99, 0
	global_load_dword v154, v204, s[98:99] nt
	s_add_u32 s98, s98, 0x6000
	s_addc_u32 s99, s99, 0
	global_load_dword v155, v204, s[98:99] nt
	s_add_u32 s98, s98, 0x6000
	s_addc_u32 s99, s99, 0
	global_load_dword v156, v204, s[98:99] nt
	s_add_u32 s98, s98, 0x6000
	s_addc_u32 s99, s99, 0
	global_load_dword v157, v204, s[98:99] nt
	s_add_u32 s98, s98, 0x6000
	s_addc_u32 s99, s99, 0
	global_load_dword v158, v204, s[98:99] nt
	s_add_u32 s98, s98, 0x6000
	s_addc_u32 s99, s99, 0
	global_load_dword v159, v204, s[98:99] nt
	s_add_u32 s98, s98, 0x6000
	s_addc_u32 s99, s99, 0
	global_load_dword v160, v204, s[98:99] nt
	s_add_u32 s98, s98, 0x6000
	s_addc_u32 s99, s99, 0
	global_load_dword v161, v204, s[98:99] nt
	s_add_u32 s98, s98, 0x6000
	s_addc_u32 s99, s99, 0
	global_load_dword v162, v204, s[98:99] nt
	s_add_u32 s98, s98, 0x6000
	s_addc_u32 s99, s99, 0
	global_load_dword v163, v204, s[98:99] nt
	s_add_u32 s98, s98, 0x6000
	s_addc_u32 s99, s99, 0
	ds_read_b128 v[164:167], v13 offset:0
	ds_read_b128 v[168:171], v13 offset:4096
	ds_read_b128 v[172:175], v13 offset:8192
	ds_read_b128 v[176:179], v13 offset:12288
	ds_read_b128 v[180:183], v13 offset:16384
	ds_read_b128 v[184:187], v13 offset:16
	ds_read_b128 v[188:191], v13 offset:4112
	ds_read_b128 v[192:195], v13 offset:8208
	ds_read_b128 v[196:199], v13 offset:12304
	ds_read_b128 v[200:203], v13 offset:16400
	s_waitcnt vmcnt(60) lgkmcnt(5)
	v_fmac_f32_e32 v8, v164, v100
	v_fmac_f32_e32 v21, v168, v100
	v_fmac_f32_e32 v20, v172, v100
	v_fmac_f32_e32 v19, v176, v100
	v_fmac_f32_e32 v18, v180, v100
	v_fmac_f32_e32 v8, v165, v101
	v_fmac_f32_e32 v21, v169, v101
	v_fmac_f32_e32 v20, v173, v101
	v_fmac_f32_e32 v19, v177, v101
	v_fmac_f32_e32 v18, v181, v101
	v_fmac_f32_e32 v8, v166, v102
	v_fmac_f32_e32 v21, v170, v102
	v_fmac_f32_e32 v20, v174, v102
	v_fmac_f32_e32 v19, v178, v102
	v_fmac_f32_e32 v18, v182, v102
	v_fmac_f32_e32 v8, v167, v103
	v_fmac_f32_e32 v21, v171, v103
	v_fmac_f32_e32 v20, v175, v103
	v_fmac_f32_e32 v19, v179, v103
	v_fmac_f32_e32 v18, v183, v103
	global_load_dword v100, v204, s[98:99] nt
	s_add_u32 s98, s98, 0x6000
	s_addc_u32 s99, s99, 0
	global_load_dword v101, v204, s[98:99] nt
	s_add_u32 s98, s98, 0x6000
	s_addc_u32 s99, s99, 0
	global_load_dword v102, v204, s[98:99] nt
	s_add_u32 s98, s98, 0x6000
	s_addc_u32 s99, s99, 0
	global_load_dword v103, v204, s[98:99] nt
	s_add_u32 s98, s98, 0x6000
	s_addc_u32 s99, s99, 0
	ds_read_b128 v[164:167], v13 offset:32
	ds_read_b128 v[168:171], v13 offset:4128
	ds_read_b128 v[172:175], v13 offset:8224
	ds_read_b128 v[176:179], v13 offset:12320
	ds_read_b128 v[180:183], v13 offset:16416
	s_waitcnt vmcnt(60) lgkmcnt(5)
	v_fmac_f32_e32 v8, v184, v104
	v_fmac_f32_e32 v21, v188, v104
	v_fmac_f32_e32 v20, v192, v104
	v_fmac_f32_e32 v19, v196, v104
	v_fmac_f32_e32 v18, v200, v104
	v_fmac_f32_e32 v8, v185, v105
	v_fmac_f32_e32 v21, v189, v105
	v_fmac_f32_e32 v20, v193, v105
	v_fmac_f32_e32 v19, v197, v105
	v_fmac_f32_e32 v18, v201, v105
	v_fmac_f32_e32 v8, v186, v106
	v_fmac_f32_e32 v21, v190, v106
	v_fmac_f32_e32 v20, v194, v106
	v_fmac_f32_e32 v19, v198, v106
	v_fmac_f32_e32 v18, v202, v106
	v_fmac_f32_e32 v8, v187, v107
	v_fmac_f32_e32 v21, v191, v107
	v_fmac_f32_e32 v20, v195, v107
	v_fmac_f32_e32 v19, v199, v107
	v_fmac_f32_e32 v18, v203, v107
	global_load_dword v104, v204, s[98:99] nt
	s_add_u32 s98, s98, 0x6000
	s_addc_u32 s99, s99, 0
	global_load_dword v105, v204, s[98:99] nt
	s_add_u32 s98, s98, 0x6000
	s_addc_u32 s99, s99, 0
	global_load_dword v106, v204, s[98:99] nt
	s_add_u32 s98, s98, 0x6000
	s_addc_u32 s99, s99, 0
	global_load_dword v107, v204, s[98:99] nt
	s_add_u32 s98, s98, 0x6000
	s_addc_u32 s99, s99, 0
	ds_read_b128 v[184:187], v13 offset:48
	ds_read_b128 v[188:191], v13 offset:4144
	ds_read_b128 v[192:195], v13 offset:8240
	ds_read_b128 v[196:199], v13 offset:12336
	ds_read_b128 v[200:203], v13 offset:16432
	s_waitcnt vmcnt(60) lgkmcnt(5)
	v_fmac_f32_e32 v8, v164, v108
	v_fmac_f32_e32 v21, v168, v108
	v_fmac_f32_e32 v20, v172, v108
	v_fmac_f32_e32 v19, v176, v108
	v_fmac_f32_e32 v18, v180, v108
	v_fmac_f32_e32 v8, v165, v109
	v_fmac_f32_e32 v21, v169, v109
	v_fmac_f32_e32 v20, v173, v109
	v_fmac_f32_e32 v19, v177, v109
	v_fmac_f32_e32 v18, v181, v109
	v_fmac_f32_e32 v8, v166, v110
	v_fmac_f32_e32 v21, v170, v110
	v_fmac_f32_e32 v20, v174, v110
	v_fmac_f32_e32 v19, v178, v110
	v_fmac_f32_e32 v18, v182, v110
	v_fmac_f32_e32 v8, v167, v111
	v_fmac_f32_e32 v21, v171, v111
	v_fmac_f32_e32 v20, v175, v111
	v_fmac_f32_e32 v19, v179, v111
	v_fmac_f32_e32 v18, v183, v111
	global_load_dword v108, v204, s[98:99] nt
	s_add_u32 s98, s98, 0x6000
	s_addc_u32 s99, s99, 0
	global_load_dword v109, v204, s[98:99] nt
	s_add_u32 s98, s98, 0x6000
	s_addc_u32 s99, s99, 0
	global_load_dword v110, v204, s[98:99] nt
	s_add_u32 s98, s98, 0x6000
	s_addc_u32 s99, s99, 0
	global_load_dword v111, v204, s[98:99] nt
	s_add_u32 s98, s98, 0x6000
	s_addc_u32 s99, s99, 0
	ds_read_b128 v[164:167], v13 offset:64
	ds_read_b128 v[168:171], v13 offset:4160
	ds_read_b128 v[172:175], v13 offset:8256
	ds_read_b128 v[176:179], v13 offset:12352
	ds_read_b128 v[180:183], v13 offset:16448
	s_waitcnt vmcnt(60) lgkmcnt(5)
	v_fmac_f32_e32 v8, v184, v112
	v_fmac_f32_e32 v21, v188, v112
	v_fmac_f32_e32 v20, v192, v112
	v_fmac_f32_e32 v19, v196, v112
	v_fmac_f32_e32 v18, v200, v112
	v_fmac_f32_e32 v8, v185, v113
	v_fmac_f32_e32 v21, v189, v113
	v_fmac_f32_e32 v20, v193, v113
	v_fmac_f32_e32 v19, v197, v113
	v_fmac_f32_e32 v18, v201, v113
	v_fmac_f32_e32 v8, v186, v114
	v_fmac_f32_e32 v21, v190, v114
	v_fmac_f32_e32 v20, v194, v114
	v_fmac_f32_e32 v19, v198, v114
	v_fmac_f32_e32 v18, v202, v114
	v_fmac_f32_e32 v8, v187, v115
	v_fmac_f32_e32 v21, v191, v115
	v_fmac_f32_e32 v20, v195, v115
	v_fmac_f32_e32 v19, v199, v115
	v_fmac_f32_e32 v18, v203, v115
	global_load_dword v112, v204, s[98:99] nt
	s_add_u32 s98, s98, 0x6000
	s_addc_u32 s99, s99, 0
	global_load_dword v113, v204, s[98:99] nt
	s_add_u32 s98, s98, 0x6000
	s_addc_u32 s99, s99, 0
	global_load_dword v114, v204, s[98:99] nt
	s_add_u32 s98, s98, 0x6000
	s_addc_u32 s99, s99, 0
	global_load_dword v115, v204, s[98:99] nt
	s_add_u32 s98, s98, 0x6000
	s_addc_u32 s99, s99, 0
	ds_read_b128 v[184:187], v13 offset:80
	ds_read_b128 v[188:191], v13 offset:4176
	ds_read_b128 v[192:195], v13 offset:8272
	ds_read_b128 v[196:199], v13 offset:12368
	ds_read_b128 v[200:203], v13 offset:16464
	s_waitcnt vmcnt(60) lgkmcnt(5)
	v_fmac_f32_e32 v8, v164, v116
	v_fmac_f32_e32 v21, v168, v116
	v_fmac_f32_e32 v20, v172, v116
	v_fmac_f32_e32 v19, v176, v116
	v_fmac_f32_e32 v18, v180, v116
	v_fmac_f32_e32 v8, v165, v117
	v_fmac_f32_e32 v21, v169, v117
	v_fmac_f32_e32 v20, v173, v117
	v_fmac_f32_e32 v19, v177, v117
	v_fmac_f32_e32 v18, v181, v117
	v_fmac_f32_e32 v8, v166, v118
	v_fmac_f32_e32 v21, v170, v118
	v_fmac_f32_e32 v20, v174, v118
	v_fmac_f32_e32 v19, v178, v118
	v_fmac_f32_e32 v18, v182, v118
	v_fmac_f32_e32 v8, v167, v119
	v_fmac_f32_e32 v21, v171, v119
	v_fmac_f32_e32 v20, v175, v119
	v_fmac_f32_e32 v19, v179, v119
	v_fmac_f32_e32 v18, v183, v119
	global_load_dword v116, v204, s[98:99] nt
	s_add_u32 s98, s98, 0x6000
	s_addc_u32 s99, s99, 0
	global_load_dword v117, v204, s[98:99] nt
	s_add_u32 s98, s98, 0x6000
	s_addc_u32 s99, s99, 0
	global_load_dword v118, v204, s[98:99] nt
	s_add_u32 s98, s98, 0x6000
	s_addc_u32 s99, s99, 0
	global_load_dword v119, v204, s[98:99] nt
	s_add_u32 s98, s98, 0x6000
	s_addc_u32 s99, s99, 0
	ds_read_b128 v[164:167], v13 offset:96
	ds_read_b128 v[168:171], v13 offset:4192
	ds_read_b128 v[172:175], v13 offset:8288
	ds_read_b128 v[176:179], v13 offset:12384
	ds_read_b128 v[180:183], v13 offset:16480
	s_waitcnt vmcnt(60) lgkmcnt(5)
	v_fmac_f32_e32 v8, v184, v120
	v_fmac_f32_e32 v21, v188, v120
	v_fmac_f32_e32 v20, v192, v120
	v_fmac_f32_e32 v19, v196, v120
	v_fmac_f32_e32 v18, v200, v120
	v_fmac_f32_e32 v8, v185, v121
	v_fmac_f32_e32 v21, v189, v121
	v_fmac_f32_e32 v20, v193, v121
	v_fmac_f32_e32 v19, v197, v121
	v_fmac_f32_e32 v18, v201, v121
	v_fmac_f32_e32 v8, v186, v122
	v_fmac_f32_e32 v21, v190, v122
	v_fmac_f32_e32 v20, v194, v122
	v_fmac_f32_e32 v19, v198, v122
	v_fmac_f32_e32 v18, v202, v122
	v_fmac_f32_e32 v8, v187, v123
	v_fmac_f32_e32 v21, v191, v123
	v_fmac_f32_e32 v20, v195, v123
	v_fmac_f32_e32 v19, v199, v123
	v_fmac_f32_e32 v18, v203, v123
	global_load_dword v120, v204, s[98:99] nt
	s_add_u32 s98, s98, 0x6000
	s_addc_u32 s99, s99, 0
	global_load_dword v121, v204, s[98:99] nt
	s_add_u32 s98, s98, 0x6000
	s_addc_u32 s99, s99, 0
	global_load_dword v122, v204, s[98:99] nt
	s_add_u32 s98, s98, 0x6000
	s_addc_u32 s99, s99, 0
	global_load_dword v123, v204, s[98:99] nt
	s_add_u32 s98, s98, 0x6000
	s_addc_u32 s99, s99, 0
	ds_read_b128 v[184:187], v13 offset:112
	ds_read_b128 v[188:191], v13 offset:4208
	ds_read_b128 v[192:195], v13 offset:8304
	ds_read_b128 v[196:199], v13 offset:12400
	ds_read_b128 v[200:203], v13 offset:16496
	s_waitcnt vmcnt(60) lgkmcnt(5)
	v_fmac_f32_e32 v8, v164, v124
	v_fmac_f32_e32 v21, v168, v124
	v_fmac_f32_e32 v20, v172, v124
	v_fmac_f32_e32 v19, v176, v124
	v_fmac_f32_e32 v18, v180, v124
	v_fmac_f32_e32 v8, v165, v125
	v_fmac_f32_e32 v21, v169, v125
	v_fmac_f32_e32 v20, v173, v125
	v_fmac_f32_e32 v19, v177, v125
	v_fmac_f32_e32 v18, v181, v125
	v_fmac_f32_e32 v8, v166, v126
	v_fmac_f32_e32 v21, v170, v126
	v_fmac_f32_e32 v20, v174, v126
	v_fmac_f32_e32 v19, v178, v126
	v_fmac_f32_e32 v18, v182, v126
	v_fmac_f32_e32 v8, v167, v127
	v_fmac_f32_e32 v21, v171, v127
	v_fmac_f32_e32 v20, v175, v127
	v_fmac_f32_e32 v19, v179, v127
	v_fmac_f32_e32 v18, v183, v127
	global_load_dword v124, v204, s[98:99] nt
	s_add_u32 s98, s98, 0x6000
	s_addc_u32 s99, s99, 0
	global_load_dword v125, v204, s[98:99] nt
	s_add_u32 s98, s98, 0x6000
	s_addc_u32 s99, s99, 0
	global_load_dword v126, v204, s[98:99] nt
	s_add_u32 s98, s98, 0x6000
	s_addc_u32 s99, s99, 0
	global_load_dword v127, v204, s[98:99] nt
	s_add_u32 s98, s98, 0x6000
	s_addc_u32 s99, s99, 0
	ds_read_b128 v[164:167], v13 offset:128
	ds_read_b128 v[168:171], v13 offset:4224
	ds_read_b128 v[172:175], v13 offset:8320
	ds_read_b128 v[176:179], v13 offset:12416
	ds_read_b128 v[180:183], v13 offset:16512
	s_waitcnt vmcnt(60) lgkmcnt(5)
	v_fmac_f32_e32 v8, v184, v128
	v_fmac_f32_e32 v21, v188, v128
	v_fmac_f32_e32 v20, v192, v128
	v_fmac_f32_e32 v19, v196, v128
	v_fmac_f32_e32 v18, v200, v128
	v_fmac_f32_e32 v8, v185, v129
	v_fmac_f32_e32 v21, v189, v129
	v_fmac_f32_e32 v20, v193, v129
	v_fmac_f32_e32 v19, v197, v129
	v_fmac_f32_e32 v18, v201, v129
	v_fmac_f32_e32 v8, v186, v130
	v_fmac_f32_e32 v21, v190, v130
	v_fmac_f32_e32 v20, v194, v130
	v_fmac_f32_e32 v19, v198, v130
	v_fmac_f32_e32 v18, v202, v130
	v_fmac_f32_e32 v8, v187, v131
	v_fmac_f32_e32 v21, v191, v131
	v_fmac_f32_e32 v20, v195, v131
	v_fmac_f32_e32 v19, v199, v131
	v_fmac_f32_e32 v18, v203, v131
	global_load_dword v128, v204, s[98:99] nt
	s_add_u32 s98, s98, 0x6000
	s_addc_u32 s99, s99, 0
	global_load_dword v129, v204, s[98:99] nt
	s_add_u32 s98, s98, 0x6000
	s_addc_u32 s99, s99, 0
	global_load_dword v130, v204, s[98:99] nt
	s_add_u32 s98, s98, 0x6000
	s_addc_u32 s99, s99, 0
	global_load_dword v131, v204, s[98:99] nt
	s_add_u32 s98, s98, 0x6000
	s_addc_u32 s99, s99, 0
	ds_read_b128 v[184:187], v13 offset:144
	ds_read_b128 v[188:191], v13 offset:4240
	ds_read_b128 v[192:195], v13 offset:8336
	ds_read_b128 v[196:199], v13 offset:12432
	ds_read_b128 v[200:203], v13 offset:16528
	s_waitcnt vmcnt(60) lgkmcnt(5)
	v_fmac_f32_e32 v8, v164, v132
	v_fmac_f32_e32 v21, v168, v132
	v_fmac_f32_e32 v20, v172, v132
	v_fmac_f32_e32 v19, v176, v132
	v_fmac_f32_e32 v18, v180, v132
	v_fmac_f32_e32 v8, v165, v133
	v_fmac_f32_e32 v21, v169, v133
	v_fmac_f32_e32 v20, v173, v133
	v_fmac_f32_e32 v19, v177, v133
	v_fmac_f32_e32 v18, v181, v133
	v_fmac_f32_e32 v8, v166, v134
	v_fmac_f32_e32 v21, v170, v134
	v_fmac_f32_e32 v20, v174, v134
	v_fmac_f32_e32 v19, v178, v134
	v_fmac_f32_e32 v18, v182, v134
	v_fmac_f32_e32 v8, v167, v135
	v_fmac_f32_e32 v21, v171, v135
	v_fmac_f32_e32 v20, v175, v135
	v_fmac_f32_e32 v19, v179, v135
	v_fmac_f32_e32 v18, v183, v135
	global_load_dword v132, v204, s[98:99] nt
	s_add_u32 s98, s98, 0x6000
	s_addc_u32 s99, s99, 0
	global_load_dword v133, v204, s[98:99] nt
	s_add_u32 s98, s98, 0x6000
	s_addc_u32 s99, s99, 0
	global_load_dword v134, v204, s[98:99] nt
	s_add_u32 s98, s98, 0x6000
	s_addc_u32 s99, s99, 0
	global_load_dword v135, v204, s[98:99] nt
	s_add_u32 s98, s98, 0x6000
	s_addc_u32 s99, s99, 0
	ds_read_b128 v[164:167], v13 offset:160
	ds_read_b128 v[168:171], v13 offset:4256
	ds_read_b128 v[172:175], v13 offset:8352
	ds_read_b128 v[176:179], v13 offset:12448
	ds_read_b128 v[180:183], v13 offset:16544
	s_waitcnt vmcnt(60) lgkmcnt(5)
	v_fmac_f32_e32 v8, v184, v136
	v_fmac_f32_e32 v21, v188, v136
	v_fmac_f32_e32 v20, v192, v136
	v_fmac_f32_e32 v19, v196, v136
	v_fmac_f32_e32 v18, v200, v136
	v_fmac_f32_e32 v8, v185, v137
	v_fmac_f32_e32 v21, v189, v137
	v_fmac_f32_e32 v20, v193, v137
	v_fmac_f32_e32 v19, v197, v137
	v_fmac_f32_e32 v18, v201, v137
	v_fmac_f32_e32 v8, v186, v138
	v_fmac_f32_e32 v21, v190, v138
	v_fmac_f32_e32 v20, v194, v138
	v_fmac_f32_e32 v19, v198, v138
	v_fmac_f32_e32 v18, v202, v138
	v_fmac_f32_e32 v8, v187, v139
	v_fmac_f32_e32 v21, v191, v139
	v_fmac_f32_e32 v20, v195, v139
	v_fmac_f32_e32 v19, v199, v139
	v_fmac_f32_e32 v18, v203, v139
	global_load_dword v136, v204, s[98:99] nt
	s_add_u32 s98, s98, 0x6000
	s_addc_u32 s99, s99, 0
	global_load_dword v137, v204, s[98:99] nt
	s_add_u32 s98, s98, 0x6000
	s_addc_u32 s99, s99, 0
	global_load_dword v138, v204, s[98:99] nt
	s_add_u32 s98, s98, 0x6000
	s_addc_u32 s99, s99, 0
	global_load_dword v139, v204, s[98:99] nt
	s_add_u32 s98, s98, 0x6000
	s_addc_u32 s99, s99, 0
	ds_read_b128 v[184:187], v13 offset:176
	ds_read_b128 v[188:191], v13 offset:4272
	ds_read_b128 v[192:195], v13 offset:8368
	ds_read_b128 v[196:199], v13 offset:12464
	ds_read_b128 v[200:203], v13 offset:16560
	s_waitcnt vmcnt(60) lgkmcnt(5)
	v_fmac_f32_e32 v8, v164, v140
	v_fmac_f32_e32 v21, v168, v140
	v_fmac_f32_e32 v20, v172, v140
	v_fmac_f32_e32 v19, v176, v140
	v_fmac_f32_e32 v18, v180, v140
	v_fmac_f32_e32 v8, v165, v141
	v_fmac_f32_e32 v21, v169, v141
	v_fmac_f32_e32 v20, v173, v141
	v_fmac_f32_e32 v19, v177, v141
	v_fmac_f32_e32 v18, v181, v141
	v_fmac_f32_e32 v8, v166, v142
	v_fmac_f32_e32 v21, v170, v142
	v_fmac_f32_e32 v20, v174, v142
	v_fmac_f32_e32 v19, v178, v142
	v_fmac_f32_e32 v18, v182, v142
	v_fmac_f32_e32 v8, v167, v143
	v_fmac_f32_e32 v21, v171, v143
	v_fmac_f32_e32 v20, v175, v143
	v_fmac_f32_e32 v19, v179, v143
	v_fmac_f32_e32 v18, v183, v143
	global_load_dword v140, v204, s[98:99] nt
	s_add_u32 s98, s98, 0x6000
	s_addc_u32 s99, s99, 0
	global_load_dword v141, v204, s[98:99] nt
	s_add_u32 s98, s98, 0x6000
	s_addc_u32 s99, s99, 0
	global_load_dword v142, v204, s[98:99] nt
	s_add_u32 s98, s98, 0x6000
	s_addc_u32 s99, s99, 0
	global_load_dword v143, v204, s[98:99] nt
	s_add_u32 s98, s98, 0x6000
	s_addc_u32 s99, s99, 0
	ds_read_b128 v[164:167], v13 offset:192
	ds_read_b128 v[168:171], v13 offset:4288
	ds_read_b128 v[172:175], v13 offset:8384
	ds_read_b128 v[176:179], v13 offset:12480
	ds_read_b128 v[180:183], v13 offset:16576
	s_waitcnt vmcnt(60) lgkmcnt(5)
	v_fmac_f32_e32 v8, v184, v144
	v_fmac_f32_e32 v21, v188, v144
	v_fmac_f32_e32 v20, v192, v144
	v_fmac_f32_e32 v19, v196, v144
	v_fmac_f32_e32 v18, v200, v144
	v_fmac_f32_e32 v8, v185, v145
	v_fmac_f32_e32 v21, v189, v145
	v_fmac_f32_e32 v20, v193, v145
	v_fmac_f32_e32 v19, v197, v145
	v_fmac_f32_e32 v18, v201, v145
	v_fmac_f32_e32 v8, v186, v146
	v_fmac_f32_e32 v21, v190, v146
	v_fmac_f32_e32 v20, v194, v146
	v_fmac_f32_e32 v19, v198, v146
	v_fmac_f32_e32 v18, v202, v146
	v_fmac_f32_e32 v8, v187, v147
	v_fmac_f32_e32 v21, v191, v147
	v_fmac_f32_e32 v20, v195, v147
	v_fmac_f32_e32 v19, v199, v147
	v_fmac_f32_e32 v18, v203, v147
	global_load_dword v144, v204, s[98:99] nt
	s_add_u32 s98, s98, 0x6000
	s_addc_u32 s99, s99, 0
	global_load_dword v145, v204, s[98:99] nt
	s_add_u32 s98, s98, 0x6000
	s_addc_u32 s99, s99, 0
	global_load_dword v146, v204, s[98:99] nt
	s_add_u32 s98, s98, 0x6000
	s_addc_u32 s99, s99, 0
	global_load_dword v147, v204, s[98:99] nt
	s_add_u32 s98, s98, 0x6000
	s_addc_u32 s99, s99, 0
	ds_read_b128 v[184:187], v13 offset:208
	ds_read_b128 v[188:191], v13 offset:4304
	ds_read_b128 v[192:195], v13 offset:8400
	ds_read_b128 v[196:199], v13 offset:12496
	ds_read_b128 v[200:203], v13 offset:16592
	s_waitcnt vmcnt(60) lgkmcnt(5)
	v_fmac_f32_e32 v8, v164, v148
	v_fmac_f32_e32 v21, v168, v148
	v_fmac_f32_e32 v20, v172, v148
	v_fmac_f32_e32 v19, v176, v148
	v_fmac_f32_e32 v18, v180, v148
	v_fmac_f32_e32 v8, v165, v149
	v_fmac_f32_e32 v21, v169, v149
	v_fmac_f32_e32 v20, v173, v149
	v_fmac_f32_e32 v19, v177, v149
	v_fmac_f32_e32 v18, v181, v149
	v_fmac_f32_e32 v8, v166, v150
	v_fmac_f32_e32 v21, v170, v150
	v_fmac_f32_e32 v20, v174, v150
	v_fmac_f32_e32 v19, v178, v150
	v_fmac_f32_e32 v18, v182, v150
	v_fmac_f32_e32 v8, v167, v151
	v_fmac_f32_e32 v21, v171, v151
	v_fmac_f32_e32 v20, v175, v151
	v_fmac_f32_e32 v19, v179, v151
	v_fmac_f32_e32 v18, v183, v151
	global_load_dword v148, v204, s[98:99] nt
	s_add_u32 s98, s98, 0x6000
	s_addc_u32 s99, s99, 0
	global_load_dword v149, v204, s[98:99] nt
	s_add_u32 s98, s98, 0x6000
	s_addc_u32 s99, s99, 0
	global_load_dword v150, v204, s[98:99] nt
	s_add_u32 s98, s98, 0x6000
	s_addc_u32 s99, s99, 0
	global_load_dword v151, v204, s[98:99] nt
	s_add_u32 s98, s98, 0x6000
	s_addc_u32 s99, s99, 0
	ds_read_b128 v[164:167], v13 offset:224
	ds_read_b128 v[168:171], v13 offset:4320
	ds_read_b128 v[172:175], v13 offset:8416
	ds_read_b128 v[176:179], v13 offset:12512
	ds_read_b128 v[180:183], v13 offset:16608
	s_waitcnt vmcnt(60) lgkmcnt(5)
	v_fmac_f32_e32 v8, v184, v152
	v_fmac_f32_e32 v21, v188, v152
	v_fmac_f32_e32 v20, v192, v152
	v_fmac_f32_e32 v19, v196, v152
	v_fmac_f32_e32 v18, v200, v152
	v_fmac_f32_e32 v8, v185, v153
	v_fmac_f32_e32 v21, v189, v153
	v_fmac_f32_e32 v20, v193, v153
	v_fmac_f32_e32 v19, v197, v153
	v_fmac_f32_e32 v18, v201, v153
	v_fmac_f32_e32 v8, v186, v154
	v_fmac_f32_e32 v21, v190, v154
	v_fmac_f32_e32 v20, v194, v154
	v_fmac_f32_e32 v19, v198, v154
	v_fmac_f32_e32 v18, v202, v154
	v_fmac_f32_e32 v8, v187, v155
	v_fmac_f32_e32 v21, v191, v155
	v_fmac_f32_e32 v20, v195, v155
	v_fmac_f32_e32 v19, v199, v155
	v_fmac_f32_e32 v18, v203, v155
	global_load_dword v152, v204, s[98:99] nt
	s_add_u32 s98, s98, 0x6000
	s_addc_u32 s99, s99, 0
	global_load_dword v153, v204, s[98:99] nt
	s_add_u32 s98, s98, 0x6000
	s_addc_u32 s99, s99, 0
	global_load_dword v154, v204, s[98:99] nt
	s_add_u32 s98, s98, 0x6000
	s_addc_u32 s99, s99, 0
	global_load_dword v155, v204, s[98:99] nt
	s_add_u32 s98, s98, 0x6000
	s_addc_u32 s99, s99, 0
	ds_read_b128 v[184:187], v13 offset:240
	ds_read_b128 v[188:191], v13 offset:4336
	ds_read_b128 v[192:195], v13 offset:8432
	ds_read_b128 v[196:199], v13 offset:12528
	ds_read_b128 v[200:203], v13 offset:16624
	s_waitcnt vmcnt(60) lgkmcnt(5)
	v_fmac_f32_e32 v8, v164, v156
	v_fmac_f32_e32 v21, v168, v156
	v_fmac_f32_e32 v20, v172, v156
	v_fmac_f32_e32 v19, v176, v156
	v_fmac_f32_e32 v18, v180, v156
	v_fmac_f32_e32 v8, v165, v157
	v_fmac_f32_e32 v21, v169, v157
	v_fmac_f32_e32 v20, v173, v157
	v_fmac_f32_e32 v19, v177, v157
	v_fmac_f32_e32 v18, v181, v157
	v_fmac_f32_e32 v8, v166, v158
	v_fmac_f32_e32 v21, v170, v158
	v_fmac_f32_e32 v20, v174, v158
	v_fmac_f32_e32 v19, v178, v158
	v_fmac_f32_e32 v18, v182, v158
	v_fmac_f32_e32 v8, v167, v159
	v_fmac_f32_e32 v21, v171, v159
	v_fmac_f32_e32 v20, v175, v159
	v_fmac_f32_e32 v19, v179, v159
	v_fmac_f32_e32 v18, v183, v159
	global_load_dword v156, v204, s[98:99] nt
	s_add_u32 s98, s98, 0x6000
	s_addc_u32 s99, s99, 0
	global_load_dword v157, v204, s[98:99] nt
	s_add_u32 s98, s98, 0x6000
	s_addc_u32 s99, s99, 0
	global_load_dword v158, v204, s[98:99] nt
	s_add_u32 s98, s98, 0x6000
	s_addc_u32 s99, s99, 0
	global_load_dword v159, v204, s[98:99] nt
	s_add_u32 s98, s98, 0x6000
	s_addc_u32 s99, s99, 0
	ds_read_b128 v[164:167], v13 offset:256
	ds_read_b128 v[168:171], v13 offset:4352
	ds_read_b128 v[172:175], v13 offset:8448
	ds_read_b128 v[176:179], v13 offset:12544
	ds_read_b128 v[180:183], v13 offset:16640
	s_waitcnt vmcnt(60) lgkmcnt(5)
	v_fmac_f32_e32 v8, v184, v160
	v_fmac_f32_e32 v21, v188, v160
	v_fmac_f32_e32 v20, v192, v160
	v_fmac_f32_e32 v19, v196, v160
	v_fmac_f32_e32 v18, v200, v160
	v_fmac_f32_e32 v8, v185, v161
	v_fmac_f32_e32 v21, v189, v161
	v_fmac_f32_e32 v20, v193, v161
	v_fmac_f32_e32 v19, v197, v161
	v_fmac_f32_e32 v18, v201, v161
	v_fmac_f32_e32 v8, v186, v162
	v_fmac_f32_e32 v21, v190, v162
	v_fmac_f32_e32 v20, v194, v162
	v_fmac_f32_e32 v19, v198, v162
	v_fmac_f32_e32 v18, v202, v162
	v_fmac_f32_e32 v8, v187, v163
	v_fmac_f32_e32 v21, v191, v163
	v_fmac_f32_e32 v20, v195, v163
	v_fmac_f32_e32 v19, v199, v163
	v_fmac_f32_e32 v18, v203, v163
	global_load_dword v160, v204, s[98:99] nt
	s_add_u32 s98, s98, 0x6000
	s_addc_u32 s99, s99, 0
	global_load_dword v161, v204, s[98:99] nt
	s_add_u32 s98, s98, 0x6000
	s_addc_u32 s99, s99, 0
	global_load_dword v162, v204, s[98:99] nt
	s_add_u32 s98, s98, 0x6000
	s_addc_u32 s99, s99, 0
	global_load_dword v163, v204, s[98:99] nt
	s_add_u32 s98, s98, 0x6000
	s_addc_u32 s99, s99, 0
	ds_read_b128 v[184:187], v13 offset:272
	ds_read_b128 v[188:191], v13 offset:4368
	ds_read_b128 v[192:195], v13 offset:8464
	ds_read_b128 v[196:199], v13 offset:12560
	ds_read_b128 v[200:203], v13 offset:16656
	s_waitcnt vmcnt(60) lgkmcnt(5)
	v_fmac_f32_e32 v8, v164, v100
	v_fmac_f32_e32 v21, v168, v100
	v_fmac_f32_e32 v20, v172, v100
	v_fmac_f32_e32 v19, v176, v100
	v_fmac_f32_e32 v18, v180, v100
	v_fmac_f32_e32 v8, v165, v101
	v_fmac_f32_e32 v21, v169, v101
	v_fmac_f32_e32 v20, v173, v101
	v_fmac_f32_e32 v19, v177, v101
	v_fmac_f32_e32 v18, v181, v101
	v_fmac_f32_e32 v8, v166, v102
	v_fmac_f32_e32 v21, v170, v102
	v_fmac_f32_e32 v20, v174, v102
	v_fmac_f32_e32 v19, v178, v102
	v_fmac_f32_e32 v18, v182, v102
	v_fmac_f32_e32 v8, v167, v103
	v_fmac_f32_e32 v21, v171, v103
	v_fmac_f32_e32 v20, v175, v103
	v_fmac_f32_e32 v19, v179, v103
	v_fmac_f32_e32 v18, v183, v103
	ds_read_b128 v[164:167], v13 offset:288
	ds_read_b128 v[168:171], v13 offset:4384
	ds_read_b128 v[172:175], v13 offset:8480
	ds_read_b128 v[176:179], v13 offset:12576
	ds_read_b128 v[180:183], v13 offset:16672
	s_waitcnt vmcnt(56) lgkmcnt(5)
	v_fmac_f32_e32 v8, v184, v104
	v_fmac_f32_e32 v21, v188, v104
	v_fmac_f32_e32 v20, v192, v104
	v_fmac_f32_e32 v19, v196, v104
	v_fmac_f32_e32 v18, v200, v104
	v_fmac_f32_e32 v8, v185, v105
	v_fmac_f32_e32 v21, v189, v105
	v_fmac_f32_e32 v20, v193, v105
	v_fmac_f32_e32 v19, v197, v105
	v_fmac_f32_e32 v18, v201, v105
	v_fmac_f32_e32 v8, v186, v106
	v_fmac_f32_e32 v21, v190, v106
	v_fmac_f32_e32 v20, v194, v106
	v_fmac_f32_e32 v19, v198, v106
	v_fmac_f32_e32 v18, v202, v106
	v_fmac_f32_e32 v8, v187, v107
	v_fmac_f32_e32 v21, v191, v107
	v_fmac_f32_e32 v20, v195, v107
	v_fmac_f32_e32 v19, v199, v107
	v_fmac_f32_e32 v18, v203, v107
	ds_read_b128 v[184:187], v13 offset:304
	ds_read_b128 v[188:191], v13 offset:4400
	ds_read_b128 v[192:195], v13 offset:8496
	ds_read_b128 v[196:199], v13 offset:12592
	ds_read_b128 v[200:203], v13 offset:16688
	s_waitcnt vmcnt(52) lgkmcnt(5)
	v_fmac_f32_e32 v8, v164, v108
	v_fmac_f32_e32 v21, v168, v108
	v_fmac_f32_e32 v20, v172, v108
	v_fmac_f32_e32 v19, v176, v108
	v_fmac_f32_e32 v18, v180, v108
	v_fmac_f32_e32 v8, v165, v109
	v_fmac_f32_e32 v21, v169, v109
	v_fmac_f32_e32 v20, v173, v109
	v_fmac_f32_e32 v19, v177, v109
	v_fmac_f32_e32 v18, v181, v109
	v_fmac_f32_e32 v8, v166, v110
	v_fmac_f32_e32 v21, v170, v110
	v_fmac_f32_e32 v20, v174, v110
	v_fmac_f32_e32 v19, v178, v110
	v_fmac_f32_e32 v18, v182, v110
	v_fmac_f32_e32 v8, v167, v111
	v_fmac_f32_e32 v21, v171, v111
	v_fmac_f32_e32 v20, v175, v111
	v_fmac_f32_e32 v19, v179, v111
	v_fmac_f32_e32 v18, v183, v111
	ds_read_b128 v[164:167], v13 offset:320
	ds_read_b128 v[168:171], v13 offset:4416
	ds_read_b128 v[172:175], v13 offset:8512
	ds_read_b128 v[176:179], v13 offset:12608
	ds_read_b128 v[180:183], v13 offset:16704
	s_waitcnt vmcnt(48) lgkmcnt(5)
	v_fmac_f32_e32 v8, v184, v112
	v_fmac_f32_e32 v21, v188, v112
	v_fmac_f32_e32 v20, v192, v112
	v_fmac_f32_e32 v19, v196, v112
	v_fmac_f32_e32 v18, v200, v112
	v_fmac_f32_e32 v8, v185, v113
	v_fmac_f32_e32 v21, v189, v113
	v_fmac_f32_e32 v20, v193, v113
	v_fmac_f32_e32 v19, v197, v113
	v_fmac_f32_e32 v18, v201, v113
	v_fmac_f32_e32 v8, v186, v114
	v_fmac_f32_e32 v21, v190, v114
	v_fmac_f32_e32 v20, v194, v114
	v_fmac_f32_e32 v19, v198, v114
	v_fmac_f32_e32 v18, v202, v114
	v_fmac_f32_e32 v8, v187, v115
	v_fmac_f32_e32 v21, v191, v115
	v_fmac_f32_e32 v20, v195, v115
	v_fmac_f32_e32 v19, v199, v115
	v_fmac_f32_e32 v18, v203, v115
	ds_read_b128 v[184:187], v13 offset:336
	ds_read_b128 v[188:191], v13 offset:4432
	ds_read_b128 v[192:195], v13 offset:8528
	ds_read_b128 v[196:199], v13 offset:12624
	ds_read_b128 v[200:203], v13 offset:16720
	s_waitcnt vmcnt(44) lgkmcnt(5)
	v_fmac_f32_e32 v8, v164, v116
	v_fmac_f32_e32 v21, v168, v116
	v_fmac_f32_e32 v20, v172, v116
	v_fmac_f32_e32 v19, v176, v116
	v_fmac_f32_e32 v18, v180, v116
	v_fmac_f32_e32 v8, v165, v117
	v_fmac_f32_e32 v21, v169, v117
	v_fmac_f32_e32 v20, v173, v117
	v_fmac_f32_e32 v19, v177, v117
	v_fmac_f32_e32 v18, v181, v117
	v_fmac_f32_e32 v8, v166, v118
	v_fmac_f32_e32 v21, v170, v118
	v_fmac_f32_e32 v20, v174, v118
	v_fmac_f32_e32 v19, v178, v118
	v_fmac_f32_e32 v18, v182, v118
	v_fmac_f32_e32 v8, v167, v119
	v_fmac_f32_e32 v21, v171, v119
	v_fmac_f32_e32 v20, v175, v119
	v_fmac_f32_e32 v19, v179, v119
	v_fmac_f32_e32 v18, v183, v119
	ds_read_b128 v[164:167], v13 offset:352
	ds_read_b128 v[168:171], v13 offset:4448
	ds_read_b128 v[172:175], v13 offset:8544
	ds_read_b128 v[176:179], v13 offset:12640
	ds_read_b128 v[180:183], v13 offset:16736
	s_waitcnt vmcnt(40) lgkmcnt(5)
	v_fmac_f32_e32 v8, v184, v120
	v_fmac_f32_e32 v21, v188, v120
	v_fmac_f32_e32 v20, v192, v120
	v_fmac_f32_e32 v19, v196, v120
	v_fmac_f32_e32 v18, v200, v120
	v_fmac_f32_e32 v8, v185, v121
	v_fmac_f32_e32 v21, v189, v121
	v_fmac_f32_e32 v20, v193, v121
	v_fmac_f32_e32 v19, v197, v121
	v_fmac_f32_e32 v18, v201, v121
	v_fmac_f32_e32 v8, v186, v122
	v_fmac_f32_e32 v21, v190, v122
	v_fmac_f32_e32 v20, v194, v122
	v_fmac_f32_e32 v19, v198, v122
	v_fmac_f32_e32 v18, v202, v122
	v_fmac_f32_e32 v8, v187, v123
	v_fmac_f32_e32 v21, v191, v123
	v_fmac_f32_e32 v20, v195, v123
	v_fmac_f32_e32 v19, v199, v123
	v_fmac_f32_e32 v18, v203, v123
	ds_read_b128 v[184:187], v13 offset:368
	ds_read_b128 v[188:191], v13 offset:4464
	ds_read_b128 v[192:195], v13 offset:8560
	ds_read_b128 v[196:199], v13 offset:12656
	ds_read_b128 v[200:203], v13 offset:16752
	s_waitcnt vmcnt(36) lgkmcnt(5)
	v_fmac_f32_e32 v8, v164, v124
	v_fmac_f32_e32 v21, v168, v124
	v_fmac_f32_e32 v20, v172, v124
	v_fmac_f32_e32 v19, v176, v124
	v_fmac_f32_e32 v18, v180, v124
	v_fmac_f32_e32 v8, v165, v125
	v_fmac_f32_e32 v21, v169, v125
	v_fmac_f32_e32 v20, v173, v125
	v_fmac_f32_e32 v19, v177, v125
	v_fmac_f32_e32 v18, v181, v125
	v_fmac_f32_e32 v8, v166, v126
	v_fmac_f32_e32 v21, v170, v126
	v_fmac_f32_e32 v20, v174, v126
	v_fmac_f32_e32 v19, v178, v126
	v_fmac_f32_e32 v18, v182, v126
	v_fmac_f32_e32 v8, v167, v127
	v_fmac_f32_e32 v21, v171, v127
	v_fmac_f32_e32 v20, v175, v127
	v_fmac_f32_e32 v19, v179, v127
	v_fmac_f32_e32 v18, v183, v127
	ds_read_b128 v[164:167], v13 offset:384
	ds_read_b128 v[168:171], v13 offset:4480
	ds_read_b128 v[172:175], v13 offset:8576
	ds_read_b128 v[176:179], v13 offset:12672
	ds_read_b128 v[180:183], v13 offset:16768
	s_waitcnt vmcnt(32) lgkmcnt(5)
	v_fmac_f32_e32 v8, v184, v128
	v_fmac_f32_e32 v21, v188, v128
	v_fmac_f32_e32 v20, v192, v128
	v_fmac_f32_e32 v19, v196, v128
	v_fmac_f32_e32 v18, v200, v128
	v_fmac_f32_e32 v8, v185, v129
	v_fmac_f32_e32 v21, v189, v129
	v_fmac_f32_e32 v20, v193, v129
	v_fmac_f32_e32 v19, v197, v129
	v_fmac_f32_e32 v18, v201, v129
	v_fmac_f32_e32 v8, v186, v130
	v_fmac_f32_e32 v21, v190, v130
	v_fmac_f32_e32 v20, v194, v130
	v_fmac_f32_e32 v19, v198, v130
	v_fmac_f32_e32 v18, v202, v130
	v_fmac_f32_e32 v8, v187, v131
	v_fmac_f32_e32 v21, v191, v131
	v_fmac_f32_e32 v20, v195, v131
	v_fmac_f32_e32 v19, v199, v131
	v_fmac_f32_e32 v18, v203, v131
	ds_read_b128 v[184:187], v13 offset:400
	ds_read_b128 v[188:191], v13 offset:4496
	ds_read_b128 v[192:195], v13 offset:8592
	ds_read_b128 v[196:199], v13 offset:12688
	ds_read_b128 v[200:203], v13 offset:16784
	s_waitcnt vmcnt(28) lgkmcnt(5)
	v_fmac_f32_e32 v8, v164, v132
	v_fmac_f32_e32 v21, v168, v132
	v_fmac_f32_e32 v20, v172, v132
	v_fmac_f32_e32 v19, v176, v132
	v_fmac_f32_e32 v18, v180, v132
	v_fmac_f32_e32 v8, v165, v133
	v_fmac_f32_e32 v21, v169, v133
	v_fmac_f32_e32 v20, v173, v133
	v_fmac_f32_e32 v19, v177, v133
	v_fmac_f32_e32 v18, v181, v133
	v_fmac_f32_e32 v8, v166, v134
	v_fmac_f32_e32 v21, v170, v134
	v_fmac_f32_e32 v20, v174, v134
	v_fmac_f32_e32 v19, v178, v134
	v_fmac_f32_e32 v18, v182, v134
	v_fmac_f32_e32 v8, v167, v135
	v_fmac_f32_e32 v21, v171, v135
	v_fmac_f32_e32 v20, v175, v135
	v_fmac_f32_e32 v19, v179, v135
	v_fmac_f32_e32 v18, v183, v135
	ds_read_b128 v[164:167], v13 offset:416
	ds_read_b128 v[168:171], v13 offset:4512
	ds_read_b128 v[172:175], v13 offset:8608
	ds_read_b128 v[176:179], v13 offset:12704
	ds_read_b128 v[180:183], v13 offset:16800
	s_waitcnt vmcnt(24) lgkmcnt(5)
	v_fmac_f32_e32 v8, v184, v136
	v_fmac_f32_e32 v21, v188, v136
	v_fmac_f32_e32 v20, v192, v136
	v_fmac_f32_e32 v19, v196, v136
	v_fmac_f32_e32 v18, v200, v136
	v_fmac_f32_e32 v8, v185, v137
	v_fmac_f32_e32 v21, v189, v137
	v_fmac_f32_e32 v20, v193, v137
	v_fmac_f32_e32 v19, v197, v137
	v_fmac_f32_e32 v18, v201, v137
	v_fmac_f32_e32 v8, v186, v138
	v_fmac_f32_e32 v21, v190, v138
	v_fmac_f32_e32 v20, v194, v138
	v_fmac_f32_e32 v19, v198, v138
	v_fmac_f32_e32 v18, v202, v138
	v_fmac_f32_e32 v8, v187, v139
	v_fmac_f32_e32 v21, v191, v139
	v_fmac_f32_e32 v20, v195, v139
	v_fmac_f32_e32 v19, v199, v139
	v_fmac_f32_e32 v18, v203, v139
	ds_read_b128 v[184:187], v13 offset:432
	ds_read_b128 v[188:191], v13 offset:4528
	ds_read_b128 v[192:195], v13 offset:8624
	ds_read_b128 v[196:199], v13 offset:12720
	ds_read_b128 v[200:203], v13 offset:16816
	s_waitcnt vmcnt(20) lgkmcnt(5)
	v_fmac_f32_e32 v8, v164, v140
	v_fmac_f32_e32 v21, v168, v140
	v_fmac_f32_e32 v20, v172, v140
	v_fmac_f32_e32 v19, v176, v140
	v_fmac_f32_e32 v18, v180, v140
	v_fmac_f32_e32 v8, v165, v141
	v_fmac_f32_e32 v21, v169, v141
	v_fmac_f32_e32 v20, v173, v141
	v_fmac_f32_e32 v19, v177, v141
	v_fmac_f32_e32 v18, v181, v141
	v_fmac_f32_e32 v8, v166, v142
	v_fmac_f32_e32 v21, v170, v142
	v_fmac_f32_e32 v20, v174, v142
	v_fmac_f32_e32 v19, v178, v142
	v_fmac_f32_e32 v18, v182, v142
	v_fmac_f32_e32 v8, v167, v143
	v_fmac_f32_e32 v21, v171, v143
	v_fmac_f32_e32 v20, v175, v143
	v_fmac_f32_e32 v19, v179, v143
	v_fmac_f32_e32 v18, v183, v143
	ds_read_b128 v[164:167], v13 offset:448
	ds_read_b128 v[168:171], v13 offset:4544
	ds_read_b128 v[172:175], v13 offset:8640
	ds_read_b128 v[176:179], v13 offset:12736
	ds_read_b128 v[180:183], v13 offset:16832
	s_waitcnt vmcnt(16) lgkmcnt(5)
	v_fmac_f32_e32 v8, v184, v144
	v_fmac_f32_e32 v21, v188, v144
	v_fmac_f32_e32 v20, v192, v144
	v_fmac_f32_e32 v19, v196, v144
	v_fmac_f32_e32 v18, v200, v144
	v_fmac_f32_e32 v8, v185, v145
	v_fmac_f32_e32 v21, v189, v145
	v_fmac_f32_e32 v20, v193, v145
	v_fmac_f32_e32 v19, v197, v145
	v_fmac_f32_e32 v18, v201, v145
	v_fmac_f32_e32 v8, v186, v146
	v_fmac_f32_e32 v21, v190, v146
	v_fmac_f32_e32 v20, v194, v146
	v_fmac_f32_e32 v19, v198, v146
	v_fmac_f32_e32 v18, v202, v146
	v_fmac_f32_e32 v8, v187, v147
	v_fmac_f32_e32 v21, v191, v147
	v_fmac_f32_e32 v20, v195, v147
	v_fmac_f32_e32 v19, v199, v147
	v_fmac_f32_e32 v18, v203, v147
	ds_read_b128 v[184:187], v13 offset:464
	ds_read_b128 v[188:191], v13 offset:4560
	ds_read_b128 v[192:195], v13 offset:8656
	ds_read_b128 v[196:199], v13 offset:12752
	ds_read_b128 v[200:203], v13 offset:16848
	s_waitcnt vmcnt(12) lgkmcnt(5)
	v_fmac_f32_e32 v8, v164, v148
	v_fmac_f32_e32 v21, v168, v148
	v_fmac_f32_e32 v20, v172, v148
	v_fmac_f32_e32 v19, v176, v148
	v_fmac_f32_e32 v18, v180, v148
	v_fmac_f32_e32 v8, v165, v149
	v_fmac_f32_e32 v21, v169, v149
	v_fmac_f32_e32 v20, v173, v149
	v_fmac_f32_e32 v19, v177, v149
	v_fmac_f32_e32 v18, v181, v149
	v_fmac_f32_e32 v8, v166, v150
	v_fmac_f32_e32 v21, v170, v150
	v_fmac_f32_e32 v20, v174, v150
	v_fmac_f32_e32 v19, v178, v150
	v_fmac_f32_e32 v18, v182, v150
	v_fmac_f32_e32 v8, v167, v151
	v_fmac_f32_e32 v21, v171, v151
	v_fmac_f32_e32 v20, v175, v151
	v_fmac_f32_e32 v19, v179, v151
	v_fmac_f32_e32 v18, v183, v151
	ds_read_b128 v[164:167], v13 offset:480
	ds_read_b128 v[168:171], v13 offset:4576
	ds_read_b128 v[172:175], v13 offset:8672
	ds_read_b128 v[176:179], v13 offset:12768
	ds_read_b128 v[180:183], v13 offset:16864
	s_waitcnt vmcnt(8) lgkmcnt(5)
	v_fmac_f32_e32 v8, v184, v152
	v_fmac_f32_e32 v21, v188, v152
	v_fmac_f32_e32 v20, v192, v152
	v_fmac_f32_e32 v19, v196, v152
	v_fmac_f32_e32 v18, v200, v152
	v_fmac_f32_e32 v8, v185, v153
	v_fmac_f32_e32 v21, v189, v153
	v_fmac_f32_e32 v20, v193, v153
	v_fmac_f32_e32 v19, v197, v153
	v_fmac_f32_e32 v18, v201, v153
	v_fmac_f32_e32 v8, v186, v154
	v_fmac_f32_e32 v21, v190, v154
	v_fmac_f32_e32 v20, v194, v154
	v_fmac_f32_e32 v19, v198, v154
	v_fmac_f32_e32 v18, v202, v154
	v_fmac_f32_e32 v8, v187, v155
	v_fmac_f32_e32 v21, v191, v155
	v_fmac_f32_e32 v20, v195, v155
	v_fmac_f32_e32 v19, v199, v155
	v_fmac_f32_e32 v18, v203, v155
	ds_read_b128 v[184:187], v13 offset:496
	ds_read_b128 v[188:191], v13 offset:4592
	ds_read_b128 v[192:195], v13 offset:8688
	ds_read_b128 v[196:199], v13 offset:12784
	ds_read_b128 v[200:203], v13 offset:16880
	s_waitcnt vmcnt(4) lgkmcnt(5)
	v_fmac_f32_e32 v8, v164, v156
	v_fmac_f32_e32 v21, v168, v156
	v_fmac_f32_e32 v20, v172, v156
	v_fmac_f32_e32 v19, v176, v156
	v_fmac_f32_e32 v18, v180, v156
	v_fmac_f32_e32 v8, v165, v157
	v_fmac_f32_e32 v21, v169, v157
	v_fmac_f32_e32 v20, v173, v157
	v_fmac_f32_e32 v19, v177, v157
	v_fmac_f32_e32 v18, v181, v157
	v_fmac_f32_e32 v8, v166, v158
	v_fmac_f32_e32 v21, v170, v158
	v_fmac_f32_e32 v20, v174, v158
	v_fmac_f32_e32 v19, v178, v158
	v_fmac_f32_e32 v18, v182, v158
	v_fmac_f32_e32 v8, v167, v159
	v_fmac_f32_e32 v21, v171, v159
	v_fmac_f32_e32 v20, v175, v159
	v_fmac_f32_e32 v19, v179, v159
	v_fmac_f32_e32 v18, v183, v159
	s_waitcnt vmcnt(0) lgkmcnt(0)
	v_fmac_f32_e32 v8, v184, v160
	v_fmac_f32_e32 v21, v188, v160
	v_fmac_f32_e32 v20, v192, v160
	v_fmac_f32_e32 v19, v196, v160
	v_fmac_f32_e32 v18, v200, v160
	v_fmac_f32_e32 v8, v185, v161
	v_fmac_f32_e32 v21, v189, v161
	v_fmac_f32_e32 v20, v193, v161
	v_fmac_f32_e32 v19, v197, v161
	v_fmac_f32_e32 v18, v201, v161
	v_fmac_f32_e32 v8, v186, v162
	v_fmac_f32_e32 v21, v190, v162
	v_fmac_f32_e32 v20, v194, v162
	v_fmac_f32_e32 v19, v198, v162
	v_fmac_f32_e32 v18, v202, v162
	v_fmac_f32_e32 v8, v187, v163
	v_fmac_f32_e32 v21, v191, v163
	v_fmac_f32_e32 v20, v195, v163
	v_fmac_f32_e32 v19, v199, v163
	v_fmac_f32_e32 v18, v203, v163
	v_add_u32_e32 v13, 0x5000, v3
	ds_write2_b32 v13, v8, v21 offset1:32
	ds_write2_b32 v13, v20, v19 offset0:64 offset1:96
	ds_write_b32 v3, v18 offset:20992
	s_waitcnt lgkmcnt(0)
	s_barrier
	s_and_saveexec_b64 s[14:15], s[4:5]
	s_cbranch_execz .LBB0_61
	s_mul_i32 s26, s8, 0x6000
	s_mul_hi_i32 s9, s8, 0x6000
	s_add_u32 s26, s80, s26
	s_addc_u32 s9, s81, s9
	s_lshl_b64 s[10:11], s[10:11], 2
	s_add_u32 s26, s26, s10
	s_addc_u32 s27, s9, s11
	global_load_dword v8, v12, s[26:27]
	v_add_u32_e32 v20, 0x5000, v27
	v_add_u32_e32 v28, 0x5400, v27
	v_add_u32_e32 v30, 0x5a00, v27
	v_add_u32_e32 v32, 0x5e00, v27
	v_mad_i64_i32 v[16:17], s[8:9], s8, 5, v[4:5]
	v_mov_b64_e32 v[18:19], s[6:7]
	ds_read2_b32 v[20:21], v20 offset1:160
	ds_read2_b32 v[28:29], v28 offset0:64 offset1:224
	ds_read2_b32 v[30:31], v30 offset1:160
	ds_read2_b32 v[32:33], v32 offset0:64 offset1:224
	v_mad_u64_u32 v[18:19], s[8:9], v16, s18, v[18:19]
	v_mad_i32_i24 v19, v17, s18, v19
	v_lshl_add_u64 v[16:17], v[18:19], 0, s[10:11]
	s_waitcnt lgkmcnt(3)
	v_add_f32_e32 v18, 0, v20
	v_add_f32_e32 v18, v18, v21
	s_waitcnt lgkmcnt(2)
	v_add_f32_e32 v18, v18, v28
	v_add_f32_e32 v18, v18, v29
	s_waitcnt lgkmcnt(1)
	v_add_f32_e32 v18, v18, v30
	v_add_f32_e32 v18, v18, v31
	s_waitcnt lgkmcnt(0)
	v_add_f32_e32 v18, v18, v32
	v_mov_b32_e32 v13, v9
	v_add_f32_e32 v18, v18, v33
	v_lshl_add_u64 v[16:17], v[16:17], 0, v[12:13]
	s_waitcnt vmcnt(0)
	v_add_f32_e32 v8, v18, v8
	global_store_dword v[16:17], v8, off
	s_branch .LBB0_61

.LBB0_1561:
	s_cmp_gt_i32 s44, 19
	s_cselect_b64 s[2:3], -1, 0
	s_cmp_lt_i32 s45, 20
	s_cselect_b64 s[4:5], -1, 0
	s_or_b64 s[2:3], s[2:3], s[4:5]
	s_and_b64 vcc, exec, s[2:3]
	s_cbranch_vccnz .LBB0_1621
	s_load_dword s25, s[0:1], 0xf0
	s_add_u32 s12, s0, 0xf0
	s_movk_i32 s0, 0x3000
	s_waitcnt vmcnt(4)
	v_and_b32_e32 v13, 0x3ff, v0
	s_addc_u32 s13, s1, 0
	v_cmp_gt_i32_e32 vcc, s0, v130
	s_and_saveexec_b64 s[14:15], vcc
	s_cbranch_execz .LBB0_1567
	v_mbcnt_lo_u32_b32 v2, -1, 0
	v_mbcnt_hi_u32_b32 v2, -1, v2
	v_and_b32_e32 v3, 64, v2
	v_add_u32_e32 v3, 64, v3
	v_xor_b32_e32 v4, 32, v2
	v_cmp_lt_i32_e32 vcc, v4, v3
	v_and_b32_e32 v12, 63, v13
	s_waitcnt vmcnt(2)
	v_mov_b32_e32 v15, 0
	v_cndmask_b32_e32 v4, v2, v4, vcc
	v_lshlrev_b32_e32 v48, 2, v4
	v_and_b32_e32 v4, 16, v13
	v_cmp_eq_u32_e64 s[2:3], 0, v4
	v_xor_b32_e32 v4, 16, v2
	v_cmp_lt_i32_e32 vcc, v4, v3
	v_lshlrev_b32_e32 v0, 5, v12
	v_mov_b32_e32 v1, v15
	v_cndmask_b32_e32 v4, v2, v4, vcc
	v_lshlrev_b32_e32 v49, 2, v4
	v_and_b32_e32 v4, 8, v13
	v_cmp_eq_u32_e64 s[4:5], 0, v4
	v_xor_b32_e32 v4, 8, v2
	v_cmp_lt_i32_e32 vcc, v4, v3
	v_lshlrev_b32_e32 v14, 4, v12
	v_lshl_add_u64 v[0:1], s[42:43], 0, v[0:1]
	v_cndmask_b32_e32 v4, v2, v4, vcc
	s_waitcnt vmcnt(1)
	v_lshlrev_b32_e32 v50, 2, v4
	v_and_b32_e32 v4, 4, v13
	s_waitcnt lgkmcnt(0)
	v_cmp_eq_u32_e64 s[6:7], 0, v4
	v_xor_b32_e32 v4, 4, v2
	v_cmp_lt_i32_e32 vcc, v4, v3
	s_mov_b64 s[0:1], 0x9f24000
	v_lshl_add_u64 v[16:17], v[0:1], 0, s[0:1]
	v_cndmask_b32_e32 v4, v2, v4, vcc
	v_lshlrev_b32_e32 v51, 2, v4
	v_and_b32_e32 v4, 2, v13
	v_cmp_eq_u32_e64 s[8:9], 0, v4
	v_xor_b32_e32 v4, 2, v2
	v_lshl_add_u64 v[0:1], s[42:43], 0, v[14:15]
	s_mov_b64 s[0:1], 0x3ea4000
	v_cmp_lt_i32_e32 vcc, v4, v3
	s_mov_b64 s[20:21], 0x5ea4000
	v_lshlrev_b32_e32 v14, 6, v12
	v_lshl_add_u64 v[18:19], v[0:1], 0, s[0:1]
	v_cndmask_b32_e32 v4, v2, v4, vcc
	v_lshl_add_u64 v[20:21], v[0:1], 0, s[20:21]
	v_lshl_add_u64 v[0:1], s[42:43], 0, v[14:15]
	s_mov_b64 s[20:21], 0xfb24000
	v_readlane_b32 s48, v255, 0
	s_lshl_b32 s26, s25, 2
	v_lshlrev_b32_e32 v52, 2, v4
	v_and_b32_e32 v4, 1, v13
	v_lshl_add_u64 v[22:23], v[0:1], 0, s[20:21]
	s_mov_b64 s[20:21], 0x1e000
	v_readlane_b32 s56, v255, 8
	v_readlane_b32 s57, v255, 9
	s_add_u32 s16, s42, 0x13a24000
	v_cmp_eq_u32_e64 s[10:11], 0, v4
	v_xor_b32_e32 v4, 1, v2
	v_lshl_add_u64 v[24:25], v[0:1], 0, s[20:21]
	v_readlane_b32 s58, v255, 10
	v_readlane_b32 s59, v255, 11
	s_mov_b64 s[20:21], s[56:57]
	s_addc_u32 s17, s43, 0
	v_cmp_lt_i32_e32 vcc, v4, v3
	s_mov_b64 s[22:23], s[58:59]
	v_lshl_add_u64 v[0:1], s[20:21], 0, v[14:15]
	s_mov_b64 s[20:21], 0x1000
	s_add_u32 s18, s42, 0x14024000
	v_cndmask_b32_e32 v2, v2, v4, vcc
	v_lshl_add_u64 v[28:29], v[0:1], 0, s[20:21]
	v_lshl_add_u64 v[0:1], s[22:23], 0, v[14:15]
	s_addc_u32 s19, s43, 0
	v_cmp_gt_u32_e64 s[0:1], 32, v12
	v_lshlrev_b32_e32 v53, 2, v2
	v_lshl_add_u64 v[26:27], s[40:41], 0, v[14:15]
	s_waitcnt vmcnt(0)
	v_lshl_add_u64 v[30:31], v[0:1], 0, s[20:21]
	s_mov_b64 s[20:21], 0
	s_movk_i32 s27, 0x1fff
	s_movk_i32 s28, 0x6000
	s_mov_b64 s[22:23], 0x6ea9000
	s_mov_b32 s29, 0x6ea9000
	s_mov_b32 s24, 0x3fb504f3
	v_mov_b32_e32 v14, 0x3727c5ac
	s_mov_b32 s30, 0x800000
	s_movk_i32 s31, 0x2fff
	v_mov_b32_e32 v54, 0x3d800000
	v_readlane_b32 s49, v255, 1
	v_readlane_b32 s50, v255, 2
	v_readlane_b32 s51, v255, 3
	v_readlane_b32 s52, v255, 4
	v_readlane_b32 s53, v255, 5
	v_readlane_b32 s54, v255, 6
	v_readlane_b32 s55, v255, 7
	v_readlane_b32 s60, v255, 12
	v_readlane_b32 s61, v255, 13
	v_readlane_b32 s62, v255, 14
	v_readlane_b32 s63, v255, 15
	global_load_dwordx4 v[196:199], v[28:29], off
	global_load_dwordx4 v[212:215], v[30:31], off
	global_load_dwordx4 v[200:203], v[28:29], off offset:16
	global_load_dwordx4 v[216:219], v[30:31], off offset:16
	global_load_dwordx4 v[204:207], v[28:29], off offset:32
	global_load_dwordx4 v[220:223], v[30:31], off offset:32
	global_load_dwordx4 v[208:211], v[28:29], off offset:48
	global_load_dwordx4 v[224:227], v[30:31], off offset:48

.LBB0_1565:
	s_cmp_lt_u32 s33, 64
	s_cselect_b64 vcc, -1, 0
	v_cndmask_b32_e32 v40, v56, v55, vcc
	s_add_i32 s37, s33, 1
	s_add_i32 s39, s33, 2
	s_add_i32 s41, s33, 3
	s_add_i32 s44, s33, 4
	s_add_i32 s49, s33, 5
	s_add_i32 s51, s33, 6
	s_add_i32 s53, s33, 7
	v_readlane_b32 s34, v40, s33
	v_cndmask_b32_e32 v41, v39, v38, vcc
	v_readlane_b32 s36, v40, s37
	v_readlane_b32 s38, v40, s39
	v_readlane_b32 s40, v40, s41
	v_readlane_b32 s46, v40, s44
	v_readlane_b32 s48, v40, s49
	v_readlane_b32 s50, v40, s51
	v_readlane_b32 s52, v40, s53
	s_ashr_i32 s35, s34, 31
	v_readlane_b32 s55, v41, s37
	s_ashr_i32 s37, s36, 31
	v_readlane_b32 s56, v41, s39
	s_ashr_i32 s39, s38, 31
	v_readlane_b32 s57, v41, s41
	s_ashr_i32 s41, s40, 31
	s_ashr_i32 s47, s46, 31
	v_readlane_b32 s58, v41, s49
	s_ashr_i32 s49, s48, 31
	v_readlane_b32 s59, v41, s51
	s_ashr_i32 s51, s50, 31
	v_readlane_b32 s60, v41, s53
	s_ashr_i32 s53, s52, 31
	s_lshl_b64 s[34:35], s[34:35], 10
	s_lshl_b64 s[36:37], s[36:37], 10
	s_lshl_b64 s[38:39], s[38:39], 10
	s_lshl_b64 s[40:41], s[40:41], 10
	s_lshl_b64 s[46:47], s[46:47], 10
	s_lshl_b64 s[48:49], s[48:49], 10
	s_lshl_b64 s[50:51], s[50:51], 10
	s_lshl_b64 s[52:53], s[52:53], 10
	v_lshl_add_u64 v[98:99], v[20:21], 0, s[34:35]
	v_readlane_b32 s54, v41, s33
	v_readlane_b32 s44, v41, s44
	v_lshl_add_u64 v[100:101], v[20:21], 0, s[36:37]
	v_lshl_add_u64 v[102:103], v[20:21], 0, s[38:39]
	v_lshl_add_u64 v[104:105], v[20:21], 0, s[40:41]
	v_lshl_add_u64 v[106:107], v[20:21], 0, s[46:47]
	v_lshl_add_u64 v[108:109], v[20:21], 0, s[48:49]
	v_lshl_add_u64 v[110:111], v[20:21], 0, s[50:51]
	v_lshl_add_u64 v[112:113], v[20:21], 0, s[52:53]
	global_load_dwordx4 v[40:43], v[98:99], off
	global_load_dwordx4 v[44:47], v[100:101], off
	global_load_dwordx4 v[58:61], v[102:103], off
	global_load_dwordx4 v[62:65], v[104:105], off
	global_load_dwordx4 v[66:69], v[106:107], off
	global_load_dwordx4 v[70:73], v[108:109], off
	global_load_dwordx4 v[74:77], v[110:111], off
	global_load_dwordx4 v[78:81], v[112:113], off
	v_mul_f32_e32 v82, s54, v54
	v_mul_f32_e32 v84, s55, v54
	v_mul_f32_e32 v86, s56, v54
	v_mul_f32_e32 v88, s57, v54
	v_mul_f32_e32 v90, s44, v54
	v_mul_f32_e32 v92, s58, v54
	v_mul_f32_e32 v94, s59, v54
	s_add_i32 s33, s33, 8
	v_mul_f32_e32 v96, s60, v54
	s_cmpk_eq_i32 s33, 0x80
	s_waitcnt vmcnt(7)
	v_cvt_pk_f32_fp8_e32 v[98:99], v40
	v_cvt_pk_f32_fp8_sdwa v[100:101], v40 src0_sel:WORD_1
	v_cvt_pk_f32_fp8_e32 v[102:103], v41
	v_cvt_pk_f32_fp8_sdwa v[40:41], v41 src0_sel:WORD_1
	v_cvt_pk_f32_fp8_e32 v[104:105], v42
	v_cvt_pk_f32_fp8_sdwa v[106:107], v42 src0_sel:WORD_1
	v_cvt_pk_f32_fp8_e32 v[108:109], v43
	v_cvt_pk_f32_fp8_sdwa v[42:43], v43 src0_sel:WORD_1
	s_waitcnt vmcnt(6)
	v_cvt_pk_f32_fp8_e32 v[110:111], v44
	v_cvt_pk_f32_fp8_sdwa v[112:113], v44 src0_sel:WORD_1
	v_cvt_pk_f32_fp8_e32 v[114:115], v45
	v_cvt_pk_f32_fp8_sdwa v[44:45], v45 src0_sel:WORD_1
	v_cvt_pk_f32_fp8_e32 v[116:117], v46
	v_cvt_pk_f32_fp8_sdwa v[118:119], v46 src0_sel:WORD_1
	v_cvt_pk_f32_fp8_e32 v[120:121], v47
	v_cvt_pk_f32_fp8_sdwa v[46:47], v47 src0_sel:WORD_1
	s_waitcnt vmcnt(5)
	v_cvt_pk_f32_fp8_e32 v[122:123], v58
	v_cvt_pk_f32_fp8_sdwa v[124:125], v58 src0_sel:WORD_1
	v_cvt_pk_f32_fp8_e32 v[126:127], v59
	v_cvt_pk_f32_fp8_sdwa v[58:59], v59 src0_sel:WORD_1
	v_cvt_pk_f32_fp8_e32 v[128:129], v60
	v_cvt_pk_f32_fp8_sdwa v[132:133], v60 src0_sel:WORD_1
	v_cvt_pk_f32_fp8_e32 v[134:135], v61
	v_cvt_pk_f32_fp8_sdwa v[60:61], v61 src0_sel:WORD_1
	s_waitcnt vmcnt(4)
	v_cvt_pk_f32_fp8_e32 v[136:137], v62
	v_cvt_pk_f32_fp8_sdwa v[138:139], v62 src0_sel:WORD_1
	v_cvt_pk_f32_fp8_e32 v[140:141], v63
	v_cvt_pk_f32_fp8_sdwa v[62:63], v63 src0_sel:WORD_1
	v_cvt_pk_f32_fp8_e32 v[142:143], v64
	v_cvt_pk_f32_fp8_sdwa v[144:145], v64 src0_sel:WORD_1
	v_cvt_pk_f32_fp8_e32 v[146:147], v65
	v_cvt_pk_f32_fp8_sdwa v[64:65], v65 src0_sel:WORD_1
	s_waitcnt vmcnt(3)
	v_cvt_pk_f32_fp8_e32 v[148:149], v66
	v_cvt_pk_f32_fp8_sdwa v[150:151], v66 src0_sel:WORD_1
	v_cvt_pk_f32_fp8_e32 v[152:153], v67
	v_cvt_pk_f32_fp8_sdwa v[66:67], v67 src0_sel:WORD_1
	v_cvt_pk_f32_fp8_e32 v[154:155], v68
	v_cvt_pk_f32_fp8_sdwa v[156:157], v68 src0_sel:WORD_1
	v_cvt_pk_f32_fp8_e32 v[158:159], v69
	v_cvt_pk_f32_fp8_sdwa v[68:69], v69 src0_sel:WORD_1
	v_pk_fma_f32 v[36:37], v[98:99], v[82:83], v[36:37] op_sel_hi:[1,0,1]
	v_pk_fma_f32 v[34:35], v[82:83], v[100:101], v[34:35] op_sel_hi:[0,1,1]
	v_pk_fma_f32 v[32:33], v[82:83], v[102:103], v[32:33] op_sel_hi:[0,1,1]
	v_pk_fma_f32 v[10:11], v[82:83], v[40:41], v[10:11] op_sel_hi:[0,1,1]
	v_pk_fma_f32 v[8:9], v[82:83], v[104:105], v[8:9] op_sel_hi:[0,1,1]
	v_pk_fma_f32 v[6:7], v[82:83], v[106:107], v[6:7] op_sel_hi:[0,1,1]
	v_pk_fma_f32 v[4:5], v[82:83], v[108:109], v[4:5] op_sel_hi:[0,1,1]
	v_pk_fma_f32 v[2:3], v[82:83], v[42:43], v[2:3] op_sel_hi:[0,1,1]
	s_waitcnt vmcnt(2)
	v_cvt_pk_f32_fp8_e32 v[160:161], v70
	v_cvt_pk_f32_fp8_sdwa v[162:163], v70 src0_sel:WORD_1
	v_cvt_pk_f32_fp8_e32 v[164:165], v71
	v_cvt_pk_f32_fp8_sdwa v[70:71], v71 src0_sel:WORD_1
	v_cvt_pk_f32_fp8_e32 v[166:167], v72
	v_cvt_pk_f32_fp8_sdwa v[168:169], v72 src0_sel:WORD_1
	v_cvt_pk_f32_fp8_e32 v[170:171], v73
	v_cvt_pk_f32_fp8_sdwa v[72:73], v73 src0_sel:WORD_1
	v_pk_fma_f32 v[36:37], v[110:111], v[84:85], v[36:37] op_sel_hi:[1,0,1]
	v_pk_fma_f32 v[34:35], v[84:85], v[112:113], v[34:35] op_sel_hi:[0,1,1]
	v_pk_fma_f32 v[32:33], v[84:85], v[114:115], v[32:33] op_sel_hi:[0,1,1]
	v_pk_fma_f32 v[10:11], v[84:85], v[44:45], v[10:11] op_sel_hi:[0,1,1]
	v_pk_fma_f32 v[8:9], v[84:85], v[116:117], v[8:9] op_sel_hi:[0,1,1]
	v_pk_fma_f32 v[6:7], v[84:85], v[118:119], v[6:7] op_sel_hi:[0,1,1]
	v_pk_fma_f32 v[4:5], v[84:85], v[120:121], v[4:5] op_sel_hi:[0,1,1]
	v_pk_fma_f32 v[2:3], v[84:85], v[46:47], v[2:3] op_sel_hi:[0,1,1]
	s_waitcnt vmcnt(1)
	v_cvt_pk_f32_fp8_e32 v[172:173], v74
	v_cvt_pk_f32_fp8_sdwa v[174:175], v74 src0_sel:WORD_1
	v_cvt_pk_f32_fp8_e32 v[176:177], v75
	v_cvt_pk_f32_fp8_sdwa v[74:75], v75 src0_sel:WORD_1
	v_cvt_pk_f32_fp8_e32 v[178:179], v76
	v_cvt_pk_f32_fp8_sdwa v[180:181], v76 src0_sel:WORD_1
	v_cvt_pk_f32_fp8_e32 v[182:183], v77
	v_cvt_pk_f32_fp8_sdwa v[76:77], v77 src0_sel:WORD_1
	v_pk_fma_f32 v[36:37], v[122:123], v[86:87], v[36:37] op_sel_hi:[1,0,1]
	v_pk_fma_f32 v[34:35], v[86:87], v[124:125], v[34:35] op_sel_hi:[0,1,1]
	v_pk_fma_f32 v[32:33], v[86:87], v[126:127], v[32:33] op_sel_hi:[0,1,1]
	v_pk_fma_f32 v[10:11], v[86:87], v[58:59], v[10:11] op_sel_hi:[0,1,1]
	v_pk_fma_f32 v[8:9], v[86:87], v[128:129], v[8:9] op_sel_hi:[0,1,1]
	v_pk_fma_f32 v[6:7], v[86:87], v[132:133], v[6:7] op_sel_hi:[0,1,1]
	v_pk_fma_f32 v[4:5], v[86:87], v[134:135], v[4:5] op_sel_hi:[0,1,1]
	v_pk_fma_f32 v[2:3], v[86:87], v[60:61], v[2:3] op_sel_hi:[0,1,1]
	s_waitcnt vmcnt(0)
	v_cvt_pk_f32_fp8_e32 v[184:185], v78
	v_cvt_pk_f32_fp8_sdwa v[186:187], v78 src0_sel:WORD_1
	v_cvt_pk_f32_fp8_e32 v[188:189], v79
	v_cvt_pk_f32_fp8_sdwa v[78:79], v79 src0_sel:WORD_1
	v_cvt_pk_f32_fp8_e32 v[190:191], v80
	v_cvt_pk_f32_fp8_sdwa v[192:193], v80 src0_sel:WORD_1
	v_cvt_pk_f32_fp8_e32 v[194:195], v81
	v_cvt_pk_f32_fp8_sdwa v[80:81], v81 src0_sel:WORD_1
	v_pk_fma_f32 v[36:37], v[136:137], v[88:89], v[36:37] op_sel_hi:[1,0,1]
	v_pk_fma_f32 v[34:35], v[88:89], v[138:139], v[34:35] op_sel_hi:[0,1,1]
	v_pk_fma_f32 v[32:33], v[88:89], v[140:141], v[32:33] op_sel_hi:[0,1,1]
	v_pk_fma_f32 v[10:11], v[88:89], v[62:63], v[10:11] op_sel_hi:[0,1,1]
	v_pk_fma_f32 v[8:9], v[88:89], v[142:143], v[8:9] op_sel_hi:[0,1,1]
	v_pk_fma_f32 v[6:7], v[88:89], v[144:145], v[6:7] op_sel_hi:[0,1,1]
	v_pk_fma_f32 v[4:5], v[88:89], v[146:147], v[4:5] op_sel_hi:[0,1,1]
	v_pk_fma_f32 v[2:3], v[88:89], v[64:65], v[2:3] op_sel_hi:[0,1,1]
	v_pk_fma_f32 v[36:37], v[148:149], v[90:91], v[36:37] op_sel_hi:[1,0,1]
	v_pk_fma_f32 v[34:35], v[90:91], v[150:151], v[34:35] op_sel_hi:[0,1,1]
	v_pk_fma_f32 v[32:33], v[90:91], v[152:153], v[32:33] op_sel_hi:[0,1,1]
	v_pk_fma_f32 v[10:11], v[90:91], v[66:67], v[10:11] op_sel_hi:[0,1,1]
	v_pk_fma_f32 v[8:9], v[90:91], v[154:155], v[8:9] op_sel_hi:[0,1,1]
	v_pk_fma_f32 v[6:7], v[90:91], v[156:157], v[6:7] op_sel_hi:[0,1,1]
	v_pk_fma_f32 v[4:5], v[90:91], v[158:159], v[4:5] op_sel_hi:[0,1,1]
	v_pk_fma_f32 v[2:3], v[90:91], v[68:69], v[2:3] op_sel_hi:[0,1,1]
	v_pk_fma_f32 v[36:37], v[160:161], v[92:93], v[36:37] op_sel_hi:[1,0,1]
	v_pk_fma_f32 v[34:35], v[92:93], v[162:163], v[34:35] op_sel_hi:[0,1,1]
	v_pk_fma_f32 v[32:33], v[92:93], v[164:165], v[32:33] op_sel_hi:[0,1,1]
	v_pk_fma_f32 v[10:11], v[92:93], v[70:71], v[10:11] op_sel_hi:[0,1,1]
	v_pk_fma_f32 v[8:9], v[92:93], v[166:167], v[8:9] op_sel_hi:[0,1,1]
	v_pk_fma_f32 v[6:7], v[92:93], v[168:169], v[6:7] op_sel_hi:[0,1,1]
	v_pk_fma_f32 v[4:5], v[92:93], v[170:171], v[4:5] op_sel_hi:[0,1,1]
	v_pk_fma_f32 v[2:3], v[92:93], v[72:73], v[2:3] op_sel_hi:[0,1,1]
	v_pk_fma_f32 v[36:37], v[172:173], v[94:95], v[36:37] op_sel_hi:[1,0,1]
	v_pk_fma_f32 v[34:35], v[94:95], v[174:175], v[34:35] op_sel_hi:[0,1,1]
	v_pk_fma_f32 v[32:33], v[94:95], v[176:177], v[32:33] op_sel_hi:[0,1,1]
	v_pk_fma_f32 v[10:11], v[94:95], v[74:75], v[10:11] op_sel_hi:[0,1,1]
	v_pk_fma_f32 v[8:9], v[94:95], v[178:179], v[8:9] op_sel_hi:[0,1,1]
	v_pk_fma_f32 v[6:7], v[94:95], v[180:181], v[6:7] op_sel_hi:[0,1,1]
	v_pk_fma_f32 v[4:5], v[94:95], v[182:183], v[4:5] op_sel_hi:[0,1,1]
	v_pk_fma_f32 v[2:3], v[94:95], v[76:77], v[2:3] op_sel_hi:[0,1,1]
	v_pk_fma_f32 v[36:37], v[184:185], v[96:97], v[36:37] op_sel_hi:[1,0,1]
	v_pk_fma_f32 v[34:35], v[96:97], v[186:187], v[34:35] op_sel_hi:[0,1,1]
	v_pk_fma_f32 v[32:33], v[96:97], v[188:189], v[32:33] op_sel_hi:[0,1,1]
	v_pk_fma_f32 v[10:11], v[96:97], v[78:79], v[10:11] op_sel_hi:[0,1,1]
	v_pk_fma_f32 v[8:9], v[96:97], v[190:191], v[8:9] op_sel_hi:[0,1,1]
	v_pk_fma_f32 v[6:7], v[96:97], v[192:193], v[6:7] op_sel_hi:[0,1,1]
	v_pk_fma_f32 v[4:5], v[96:97], v[194:195], v[4:5] op_sel_hi:[0,1,1]
	v_pk_fma_f32 v[2:3], v[96:97], v[80:81], v[2:3] op_sel_hi:[0,1,1]
	s_cbranch_scc0 .LBB0_1565
	v_add_u32_e32 v38, 0xffffe000, v130
	v_lshrrev_b32_e32 v38, 10, v38
	v_add_u32_e32 v38, 1, v38
	v_cmp_lt_i32_e32 vcc, s27, v130
	v_lshlrev_b64 v[80:81], 2, v[0:1]
	v_lshl_add_u64 v[0:1], v[22:23], 0, v[80:81]
	v_cndmask_b32_e32 v38, 0, v38, vcc
	v_mad_u64_u32 v[42:43], s[34:35], v38, s28, v[24:25]
	v_add_co_u32_e32 v38, vcc, s29, v42
	v_lshl_add_u64 v[46:47], v[42:43], 0, s[22:23]
	s_nop 0
	v_addc_co_u32_e32 v39, vcc, 0, v43, vcc
	global_load_dwordx4 v[38:41], v[38:39], off
	s_nop 0
	global_load_dwordx4 v[42:45], v[46:47], off offset:16
	global_load_dwordx4 v[56:59], v[46:47], off offset:32
	global_load_dwordx4 v[60:63], v[46:47], off offset:48
	global_load_dwordx4 v[64:67], v[0:1], off
	global_load_dwordx4 v[68:71], v[0:1], off offset:16
	global_load_dwordx4 v[72:75], v[0:1], off offset:32
	global_load_dwordx4 v[76:79], v[0:1], off offset:48
	v_add_u32_e32 v130, s26, v130
	s_waitcnt vmcnt(6)
	v_pk_mul_f32 v[32:33], v[32:33], v[42:43]
	v_pk_mul_f32 v[0:1], v[36:37], v[38:39]
	v_pk_mul_f32 v[34:35], v[34:35], v[40:41]
	s_waitcnt vmcnt(3)
	v_pk_fma_f32 v[36:37], v[64:65], s[24:25], v[0:1] op_sel_hi:[1,0,1]
	v_pk_fma_f32 v[34:35], v[66:67], s[24:25], v[34:35] op_sel_hi:[1,0,1]
	v_add_f32_e32 v0, 0, v36
	v_add_f32_e32 v0, v0, v37
	v_add_f32_e32 v0, v0, v34
	s_waitcnt vmcnt(2)
	v_pk_fma_f32 v[32:33], v[68:69], s[24:25], v[32:33] op_sel_hi:[1,0,1]
	v_add_f32_e32 v0, v0, v35
	v_pk_mul_f32 v[10:11], v[10:11], v[44:45]
	v_add_f32_e32 v0, v0, v32
	v_pk_fma_f32 v[10:11], v[70:71], s[24:25], v[10:11] op_sel_hi:[1,0,1]
	v_add_f32_e32 v0, v0, v33
	v_pk_mul_f32 v[8:9], v[8:9], v[56:57]
	v_add_f32_e32 v0, v0, v10
	s_waitcnt vmcnt(1)
	v_pk_fma_f32 v[8:9], v[72:73], s[24:25], v[8:9] op_sel_hi:[1,0,1]
	v_add_f32_e32 v0, v0, v11
	v_pk_mul_f32 v[6:7], v[6:7], v[58:59]
	v_add_f32_e32 v0, v0, v8
	v_pk_fma_f32 v[38:39], v[74:75], s[24:25], v[6:7] op_sel_hi:[1,0,1]
	v_add_f32_e32 v0, v0, v9
	v_pk_mul_f32 v[4:5], v[4:5], v[60:61]
	v_add_f32_e32 v0, v0, v38
	s_waitcnt vmcnt(0)
	v_pk_fma_f32 v[40:41], v[76:77], s[24:25], v[4:5] op_sel_hi:[1,0,1]
	v_add_f32_e32 v0, v0, v39
	v_pk_mul_f32 v[2:3], v[2:3], v[62:63]
	v_add_f32_e32 v0, v0, v40
	v_pk_fma_f32 v[42:43], v[78:79], s[24:25], v[2:3] op_sel_hi:[1,0,1]
	v_add_f32_e32 v0, v0, v41
	v_add_f32_e32 v0, v0, v42
	v_add_f32_e32 v0, v0, v43
	ds_bpermute_b32 v1, v48, v0
	s_waitcnt lgkmcnt(0)
	v_add_f32_e32 v0, v0, v1
	ds_bpermute_b32 v1, v49, v0
	s_waitcnt lgkmcnt(0)
	v_add_f32_e32 v0, v0, v1
	ds_bpermute_b32 v1, v50, v0
	s_waitcnt lgkmcnt(0)
	v_add_f32_e32 v0, v0, v1
	ds_bpermute_b32 v1, v51, v0
	s_waitcnt lgkmcnt(0)
	v_add_f32_e32 v0, v0, v1
	ds_bpermute_b32 v1, v52, v0
	s_waitcnt lgkmcnt(0)
	v_add_f32_e32 v44, v0, v1
	ds_bpermute_b32 v45, v53, v44
	s_waitcnt lgkmcnt(0)
	v_add_f32_e32 v44, v44, v45
	v_mul_f32_e32 v44, 0x3a800000, v44
	v_pk_add_f32 v[36:37], v[36:37], v[44:45] op_sel_hi:[1,0] neg_lo:[0,1] neg_hi:[0,1]
	v_pk_add_f32 v[34:35], v[34:35], v[44:45] op_sel_hi:[1,0] neg_lo:[0,1] neg_hi:[0,1]
	v_pk_add_f32 v[32:33], v[32:33], v[44:45] op_sel_hi:[1,0] neg_lo:[0,1] neg_hi:[0,1]
	v_pk_add_f32 v[10:11], v[10:11], v[44:45] op_sel_hi:[1,0] neg_lo:[0,1] neg_hi:[0,1]
	v_pk_add_f32 v[8:9], v[8:9], v[44:45] op_sel_hi:[1,0] neg_lo:[0,1] neg_hi:[0,1]
	v_pk_add_f32 v[38:39], v[38:39], v[44:45] op_sel_hi:[1,0] neg_lo:[0,1] neg_hi:[0,1]
	v_pk_add_f32 v[40:41], v[40:41], v[44:45] op_sel_hi:[1,0] neg_lo:[0,1] neg_hi:[0,1]
	v_pk_add_f32 v[42:43], v[42:43], v[44:45] op_sel_hi:[1,0] neg_lo:[0,1] neg_hi:[0,1]
	v_pk_mul_f32 v[44:45], v[36:37], v[36:37]
	v_pk_mul_f32 v[46:47], v[34:35], v[34:35]
	v_add_f32_e32 v44, v44, v45
	v_add_f32_e32 v44, v46, v44
	v_pk_mul_f32 v[56:57], v[32:33], v[32:33]
	v_add_f32_e32 v44, v47, v44
	v_add_f32_e32 v44, v56, v44
	v_pk_mul_f32 v[58:59], v[10:11], v[10:11]
	v_add_f32_e32 v44, v57, v44
	v_add_f32_e32 v44, v58, v44
	v_pk_mul_f32 v[60:61], v[8:9], v[8:9]
	v_add_f32_e32 v44, v59, v44
	v_add_f32_e32 v44, v60, v44
	v_pk_mul_f32 v[62:63], v[38:39], v[38:39]
	v_add_f32_e32 v44, v61, v44
	v_add_f32_e32 v44, v62, v44
	v_pk_mul_f32 v[64:65], v[40:41], v[40:41]
	v_add_f32_e32 v44, v63, v44
	v_add_f32_e32 v44, v64, v44
	v_pk_mul_f32 v[66:67], v[42:43], v[42:43]
	v_add_f32_e32 v44, v65, v44
	v_add_f32_e32 v44, v66, v44
	v_add_f32_e32 v44, v67, v44
	ds_bpermute_b32 v45, v48, v44
	s_waitcnt lgkmcnt(0)
	v_add_f32_e32 v44, v44, v45
	ds_bpermute_b32 v45, v49, v44
	s_waitcnt lgkmcnt(0)
	v_add_f32_e32 v44, v44, v45
	ds_bpermute_b32 v45, v50, v44
	s_waitcnt lgkmcnt(0)
	v_add_f32_e32 v44, v44, v45
	ds_bpermute_b32 v45, v51, v44
	s_waitcnt lgkmcnt(0)
	v_add_f32_e32 v44, v44, v45
	ds_bpermute_b32 v45, v52, v44
	s_waitcnt lgkmcnt(0)
	v_add_f32_e32 v44, v44, v45
	ds_bpermute_b32 v45, v53, v44
	s_waitcnt lgkmcnt(0)
	v_add_f32_e32 v44, v44, v45
	v_fmamk_f32 v44, v44, 0x3a800000, v14
	v_mul_f32_e32 v45, 0x4b800000, v44
	v_cmp_gt_f32_e32 vcc, s30, v44
	s_nop 1
	v_cndmask_b32_e32 v44, v44, v45, vcc
	v_rsq_f32_e32 v46, v44
	v_lshl_add_u64 v[44:45], v[26:27], 0, v[80:81]
	v_mul_f32_e32 v47, 0x45800000, v46
	v_cndmask_b32_e32 v46, v46, v47, vcc
	v_pk_mul_f32 v[36:37], v[36:37], v[46:47] op_sel_hi:[1,0]
	v_pk_mul_f32 v[34:35], v[34:35], v[46:47] op_sel_hi:[1,0]
	v_pk_fma_f32 v[0:1], v[196:197], v[36:37], v[212:213]
	v_pk_fma_f32 v[2:3], v[198:199], v[34:35], v[214:215]
	global_store_dwordx4 v[44:45], v[0:3], off
	s_nop 1
	s_nop 0
	v_pk_mul_f32 v[32:33], v[32:33], v[46:47] op_sel_hi:[1,0]
	v_pk_mul_f32 v[10:11], v[10:11], v[46:47] op_sel_hi:[1,0]
	v_pk_mul_f32 v[8:9], v[8:9], v[46:47] op_sel_hi:[1,0]
	v_cmp_lt_i32_e32 vcc, s31, v130
	s_or_b64 s[20:21], vcc, s[20:21]
	v_pk_fma_f32 v[0:1], v[200:201], v[32:33], v[216:217]
	v_pk_fma_f32 v[2:3], v[202:203], v[10:11], v[218:219]
	global_store_dwordx4 v[44:45], v[0:3], off offset:16
	s_nop 1
	s_nop 0
	v_pk_mul_f32 v[10:11], v[38:39], v[46:47] op_sel_hi:[1,0]
	v_pk_fma_f32 v[0:1], v[204:205], v[8:9], v[220:221]
	v_pk_fma_f32 v[2:3], v[206:207], v[10:11], v[222:223]
	global_store_dwordx4 v[44:45], v[0:3], off offset:32
	s_nop 1
	s_nop 0
	v_pk_mul_f32 v[8:9], v[40:41], v[46:47] op_sel_hi:[1,0]
	v_pk_mul_f32 v[10:11], v[42:43], v[46:47] op_sel_hi:[1,0]
	v_pk_fma_f32 v[0:1], v[8:9], v[208:209], v[224:225]
	v_pk_fma_f32 v[2:3], v[10:11], v[210:211], v[226:227]
	global_store_dwordx4 v[44:45], v[0:3], off offset:48
	s_nop 1
	s_andn2_b64 exec, exec, s[20:21]
	s_cbranch_execnz .LBB0_1564
